# scan step loop fully unrolled over the 32 steps of a chunk (immediate LDS offsets, no loop counter or pointer updates)
# speedup vs baseline: 1.0329x; 1.0051x over previous
; #define SC_GET(X, t) do { const float* p = rec + (t) * 320; w##X = *(const f32x4*)p; a##X = *(const f32x4*)(p + 4); b##X = *(const f32x4*)(p + 8); k##X = *(const f32x4*)(p + 12); q##X = *(const f32x4*)(p + 16); \
;                 v##X = *(const f32x4*)(VVa + (t) * 64); } while (0)
; DI void scan_phase(unsigned char* lds, const Ctx& a, const Op& d, const int variant) {
;     ...
;                 const float* base = (const float*)(lds + bi * SC_BUF);
;                 const float* rec = base + jg * 20; const float* VVa = base + 10240 + rA * 2;
;                 f32x4 wA, aA, bA, kA, qA, vA, wB, aB, bB, kB, qB, vB;
;     ...
;                 SC_GET(A, 0);
; #pragma unroll 2
;                 for (int t = 0; t < SC_T; t += 2) {
;                     SC_GET(B, t + 1);
;                     SC_STEP(A, t);
;                     if (t + 2 < SC_T) SC_GET(A, t + 2);
;                     SC_STEP(B, t + 1);
;                 }
.LBB0_453:
	s_and_b32 s48, s47, 1
	s_and_saveexec_b64 s[10:11], s[8:9]
	s_xor_b64 s[10:11], exec, s[10:11]
	s_cbranch_execz .LBB0_466
	s_mul_i32 s30, s48, 0xd000
	v_add_u32_e32 v175, s30, v157
	v_add_u32_e32 v123, s30, v158
	v_mbcnt_lo_u32_b32 v176, -1, 0
	v_mbcnt_hi_u32_b32 v176, -1, v176
	v_bfe_u32 v177, v176, 3, 1
	v_bfe_u32 v176, v176, 2, 1
	v_lshlrev_b32_e32 v177, 7, v177
	v_lshl_add_u32 v176, v176, 2, v177
	v_add3_u32 v178, v169, s30, v176
	v_cndmask_b32_e64 v176, 0, 1.0, s[4:5]
	v_mov_b32_e32 v177, v176
	s_mov_b32 s34, 0x11111111
	s_mov_b32 s35, 0x11111111
	ds_read_b128 v[40:43], v175
	ds_read_b128 v[44:47], v175 offset:16
	ds_read_b128 v[48:51], v175 offset:32
	ds_read_b128 v[52:55], v175 offset:48
	ds_read_b128 v[56:59], v175 offset:64
	ds_read_b128 v[60:63], v123 offset:40960
	s_setprio 3
	s_mov_b32 s38, 1
	s_waitcnt lgkmcnt(0)
.Lscan_steps:
	s_waitcnt lgkmcnt(1)
	v_pk_mul_f32 v[106:107], v[64:65], v[44:45] op_sel_hi:[1,0]
	ds_read_b128 v[72:75], v175 offset:1280
	v_pk_mul_f32 v[108:109], v[64:65], v[56:57] op_sel_hi:[1,0]
	ds_read_b128 v[76:79], v175 offset:1296
	v_pk_fma_f32 v[106:107], v[66:67], v[44:45], v[106:107] op_sel:[0,1,0]
	ds_read_b128 v[80:83], v175 offset:1312
	v_pk_fma_f32 v[108:109], v[66:67], v[56:57], v[108:109] op_sel:[0,1,0]
	ds_read_b128 v[84:87], v175 offset:1328
	v_pk_fma_f32 v[106:107], v[68:69], v[46:47], v[106:107] op_sel_hi:[1,0,1]
	ds_read_b128 v[88:91], v175 offset:1344
	v_pk_fma_f32 v[108:109], v[68:69], v[58:59], v[108:109] op_sel_hi:[1,0,1]
	ds_read_b128 v[92:95], v123 offset:41216
	v_pk_fma_f32 v[106:107], v[70:71], v[46:47], v[106:107] op_sel:[0,1,0]
	v_pk_fma_f32 v[108:109], v[70:71], v[58:59], v[108:109] op_sel:[0,1,0]
	v_pk_mul_f32 v[110:111], v[64:65], v[40:41] op_sel_hi:[1,0]
	v_add_f32_dpp v106, v106, v106 quad_perm:[1,0,3,2] row_mask:0xf bank_mask:0xf bound_ctrl:1
	v_add_f32_dpp v107, v107, v107 quad_perm:[1,0,3,2] row_mask:0xf bank_mask:0xf bound_ctrl:1
	v_pk_fma_f32 v[108:109], v[62:63], v[176:177], v[108:109]
	v_pk_mul_f32 v[112:113], v[66:67], v[40:41] op_sel:[0,1]
	v_add_f32_dpp v106, v106, v106 quad_perm:[2,3,0,1] row_mask:0xf bank_mask:0xf bound_ctrl:1
	v_add_f32_dpp v107, v107, v107 quad_perm:[2,3,0,1] row_mask:0xf bank_mask:0xf bound_ctrl:1
	v_add_f32_dpp v148, v108, v108 row_half_mirror row_mask:0xf bank_mask:0xf bound_ctrl:1
	v_add_f32_dpp v148, v109, v109 row_half_mirror row_mask:0xf bank_mask:0xa
	v_add_f32_dpp v106, v106, v106 row_half_mirror row_mask:0xf bank_mask:0xf bound_ctrl:1
	v_add_f32_dpp v107, v107, v107 row_half_mirror row_mask:0xf bank_mask:0xf bound_ctrl:1
	v_pk_mul_f32 v[144:145], v[68:69], v[42:43] op_sel_hi:[1,0]
	v_pk_mul_f32 v[146:147], v[70:71], v[42:43] op_sel:[0,1]
	v_add_f32_dpp v106, v106, v106 row_mirror row_mask:0xf bank_mask:0xf bound_ctrl:1
	v_add_f32_dpp v107, v107, v107 row_mirror row_mask:0xf bank_mask:0xf bound_ctrl:1
	v_pk_fma_f32 v[110:111], v[60:61], v[52:53], v[110:111] op_sel_hi:[1,0,1]
	v_pk_fma_f32 v[112:113], v[60:61], v[52:53], v[112:113] op_sel:[0,1,0]
	v_pk_fma_f32 v[144:145], v[60:61], v[54:55], v[144:145] op_sel_hi:[1,0,1]
	v_pk_fma_f32 v[146:147], v[60:61], v[54:55], v[146:147] op_sel:[0,1,0]
	v_pk_fma_f32 v[64:65], v[106:107], v[48:49], v[110:111] op_sel_hi:[1,0,1]
	v_pk_fma_f32 v[66:67], v[106:107], v[48:49], v[112:113] op_sel:[0,1,0]
	v_pk_fma_f32 v[68:69], v[106:107], v[50:51], v[144:145] op_sel_hi:[1,0,1]
	v_pk_fma_f32 v[70:71], v[106:107], v[50:51], v[146:147] op_sel:[0,1,0]
	s_waitcnt lgkmcnt(0)
	v_pk_mul_f32 v[106:107], v[64:65], v[76:77] op_sel_hi:[1,0]
	ds_read_b128 v[40:43], v175 offset:2560
	v_pk_mul_f32 v[108:109], v[64:65], v[88:89] op_sel_hi:[1,0]
	ds_read_b128 v[44:47], v175 offset:2576
	v_pk_fma_f32 v[106:107], v[66:67], v[76:77], v[106:107] op_sel:[0,1,0]
	ds_read_b128 v[48:51], v175 offset:2592
	v_pk_fma_f32 v[108:109], v[66:67], v[88:89], v[108:109] op_sel:[0,1,0]
	ds_read_b128 v[52:55], v175 offset:2608
	v_pk_fma_f32 v[106:107], v[68:69], v[78:79], v[106:107] op_sel_hi:[1,0,1]
	ds_read_b128 v[56:59], v175 offset:2624
	v_pk_fma_f32 v[108:109], v[68:69], v[90:91], v[108:109] op_sel_hi:[1,0,1]
	ds_read_b128 v[60:63], v123 offset:41472
	v_pk_fma_f32 v[106:107], v[70:71], v[78:79], v[106:107] op_sel:[0,1,0]
	v_pk_fma_f32 v[108:109], v[70:71], v[90:91], v[108:109] op_sel:[0,1,0]
	v_pk_mul_f32 v[110:111], v[64:65], v[72:73] op_sel_hi:[1,0]
	v_add_f32_dpp v106, v106, v106 quad_perm:[1,0,3,2] row_mask:0xf bank_mask:0xf bound_ctrl:1
	v_add_f32_dpp v107, v107, v107 quad_perm:[1,0,3,2] row_mask:0xf bank_mask:0xf bound_ctrl:1
	v_pk_fma_f32 v[108:109], v[94:95], v[176:177], v[108:109]
	v_pk_mul_f32 v[112:113], v[66:67], v[72:73] op_sel:[0,1]
	v_add_f32_dpp v106, v106, v106 quad_perm:[2,3,0,1] row_mask:0xf bank_mask:0xf bound_ctrl:1
	v_add_f32_dpp v107, v107, v107 quad_perm:[2,3,0,1] row_mask:0xf bank_mask:0xf bound_ctrl:1
	v_add_f32_dpp v149, v108, v108 row_half_mirror row_mask:0xf bank_mask:0xf bound_ctrl:1
	v_add_f32_dpp v149, v109, v109 row_half_mirror row_mask:0xf bank_mask:0xa
	v_add_f32_dpp v106, v106, v106 row_half_mirror row_mask:0xf bank_mask:0xf bound_ctrl:1
	v_add_f32_dpp v107, v107, v107 row_half_mirror row_mask:0xf bank_mask:0xf bound_ctrl:1
	v_pk_mul_f32 v[144:145], v[68:69], v[74:75] op_sel_hi:[1,0]
	v_pk_mul_f32 v[146:147], v[70:71], v[74:75] op_sel:[0,1]
	v_add_f32_dpp v150, v148, v148 row_ror:8 row_mask:0xf bank_mask:0xf bound_ctrl:1
	v_add_f32_dpp v150, v149, v149 row_ror:8 row_mask:0xf bank_mask:0xc
	v_add_f32_dpp v106, v106, v106 row_mirror row_mask:0xf bank_mask:0xf bound_ctrl:1
	v_add_f32_dpp v107, v107, v107 row_mirror row_mask:0xf bank_mask:0xf bound_ctrl:1
	v_pk_fma_f32 v[110:111], v[92:93], v[84:85], v[110:111] op_sel_hi:[1,0,1]
	v_pk_fma_f32 v[112:113], v[92:93], v[84:85], v[112:113] op_sel:[0,1,0]
	v_pk_fma_f32 v[144:145], v[92:93], v[86:87], v[144:145] op_sel_hi:[1,0,1]
	v_pk_fma_f32 v[146:147], v[92:93], v[86:87], v[146:147] op_sel:[0,1,0]
	v_add_f32_dpp v150, v150, v150 quad_perm:[1,0,3,2] row_mask:0xf bank_mask:0xf bound_ctrl:1
	v_pk_fma_f32 v[64:65], v[106:107], v[80:81], v[110:111] op_sel_hi:[1,0,1]
	v_pk_fma_f32 v[66:67], v[106:107], v[80:81], v[112:113] op_sel:[0,1,0]
	v_add_f32_dpp v150, v150, v150 quad_perm:[2,3,0,1] row_mask:0xf bank_mask:0xf bound_ctrl:1
	v_pk_fma_f32 v[68:69], v[106:107], v[82:83], v[144:145] op_sel_hi:[1,0,1]
	v_pk_fma_f32 v[70:71], v[106:107], v[82:83], v[146:147] op_sel:[0,1,0]
	s_mov_b64 exec, s[34:35]
	ds_write_b32 v178, v150 offset:0
	s_mov_b64 exec, -1
	s_waitcnt lgkmcnt(1)
; #define SC_GET(X, t) do { const float* p = rec + (t) * 320; w##X = *(const f32x4*)p; a##X = *(const f32x4*)(p + 4); b##X = *(const f32x4*)(p + 8); k##X = *(const f32x4*)(p + 12); q##X = *(const f32x4*)(p + 16); \
;                 v##X = *(const f32x4*)(VVa + (t) * 64); } while (0)
; DI void scan_phase(unsigned char* lds, const Ctx& a, const Op& d, const int variant) {
;     ...
;                 SC_GET(A, 0);
; #pragma unroll 2
;                 for (int t = 0; t < SC_T; t += 2) {
;                     SC_GET(B, t + 1);
;                     SC_STEP(A, t);
;                     if (t + 2 < SC_T) SC_GET(A, t + 2);
;                     SC_STEP(B, t + 1);
;                 }
	v_pk_mul_f32 v[106:107], v[64:65], v[44:45] op_sel_hi:[1,0]
	ds_read_b128 v[72:75], v175 offset:3840
	v_pk_mul_f32 v[108:109], v[64:65], v[56:57] op_sel_hi:[1,0]
	ds_read_b128 v[76:79], v175 offset:3856
	v_pk_fma_f32 v[106:107], v[66:67], v[44:45], v[106:107] op_sel:[0,1,0]
	ds_read_b128 v[80:83], v175 offset:3872
	v_pk_fma_f32 v[108:109], v[66:67], v[56:57], v[108:109] op_sel:[0,1,0]
	ds_read_b128 v[84:87], v175 offset:3888
	v_pk_fma_f32 v[106:107], v[68:69], v[46:47], v[106:107] op_sel_hi:[1,0,1]
	ds_read_b128 v[88:91], v175 offset:3904
	v_pk_fma_f32 v[108:109], v[68:69], v[58:59], v[108:109] op_sel_hi:[1,0,1]
	ds_read_b128 v[92:95], v123 offset:41728
	v_pk_fma_f32 v[106:107], v[70:71], v[46:47], v[106:107] op_sel:[0,1,0]
	v_pk_fma_f32 v[108:109], v[70:71], v[58:59], v[108:109] op_sel:[0,1,0]
	v_pk_mul_f32 v[110:111], v[64:65], v[40:41] op_sel_hi:[1,0]
	v_add_f32_dpp v106, v106, v106 quad_perm:[1,0,3,2] row_mask:0xf bank_mask:0xf bound_ctrl:1
	v_add_f32_dpp v107, v107, v107 quad_perm:[1,0,3,2] row_mask:0xf bank_mask:0xf bound_ctrl:1
	v_pk_fma_f32 v[108:109], v[62:63], v[176:177], v[108:109]
	v_pk_mul_f32 v[112:113], v[66:67], v[40:41] op_sel:[0,1]
	v_add_f32_dpp v106, v106, v106 quad_perm:[2,3,0,1] row_mask:0xf bank_mask:0xf bound_ctrl:1
	v_add_f32_dpp v107, v107, v107 quad_perm:[2,3,0,1] row_mask:0xf bank_mask:0xf bound_ctrl:1
	v_add_f32_dpp v148, v108, v108 row_half_mirror row_mask:0xf bank_mask:0xf bound_ctrl:1
	v_add_f32_dpp v148, v109, v109 row_half_mirror row_mask:0xf bank_mask:0xa
	v_add_f32_dpp v106, v106, v106 row_half_mirror row_mask:0xf bank_mask:0xf bound_ctrl:1
	v_add_f32_dpp v107, v107, v107 row_half_mirror row_mask:0xf bank_mask:0xf bound_ctrl:1
	v_pk_mul_f32 v[144:145], v[68:69], v[42:43] op_sel_hi:[1,0]
	v_pk_mul_f32 v[146:147], v[70:71], v[42:43] op_sel:[0,1]
	v_add_f32_dpp v106, v106, v106 row_mirror row_mask:0xf bank_mask:0xf bound_ctrl:1
	v_add_f32_dpp v107, v107, v107 row_mirror row_mask:0xf bank_mask:0xf bound_ctrl:1
	v_pk_fma_f32 v[110:111], v[60:61], v[52:53], v[110:111] op_sel_hi:[1,0,1]
	v_pk_fma_f32 v[112:113], v[60:61], v[52:53], v[112:113] op_sel:[0,1,0]
	v_pk_fma_f32 v[144:145], v[60:61], v[54:55], v[144:145] op_sel_hi:[1,0,1]
	v_pk_fma_f32 v[146:147], v[60:61], v[54:55], v[146:147] op_sel:[0,1,0]
	v_pk_fma_f32 v[64:65], v[106:107], v[48:49], v[110:111] op_sel_hi:[1,0,1]
	v_pk_fma_f32 v[66:67], v[106:107], v[48:49], v[112:113] op_sel:[0,1,0]
	v_pk_fma_f32 v[68:69], v[106:107], v[50:51], v[144:145] op_sel_hi:[1,0,1]
	v_pk_fma_f32 v[70:71], v[106:107], v[50:51], v[146:147] op_sel:[0,1,0]
	s_waitcnt lgkmcnt(0)
	v_pk_mul_f32 v[106:107], v[64:65], v[76:77] op_sel_hi:[1,0]
	ds_read_b128 v[40:43], v175 offset:5120
	v_pk_mul_f32 v[108:109], v[64:65], v[88:89] op_sel_hi:[1,0]
	ds_read_b128 v[44:47], v175 offset:5136
	v_pk_fma_f32 v[106:107], v[66:67], v[76:77], v[106:107] op_sel:[0,1,0]
	ds_read_b128 v[48:51], v175 offset:5152
	v_pk_fma_f32 v[108:109], v[66:67], v[88:89], v[108:109] op_sel:[0,1,0]
	ds_read_b128 v[52:55], v175 offset:5168
	v_pk_fma_f32 v[106:107], v[68:69], v[78:79], v[106:107] op_sel_hi:[1,0,1]
	ds_read_b128 v[56:59], v175 offset:5184
	v_pk_fma_f32 v[108:109], v[68:69], v[90:91], v[108:109] op_sel_hi:[1,0,1]
	ds_read_b128 v[60:63], v123 offset:41984
	v_pk_fma_f32 v[106:107], v[70:71], v[78:79], v[106:107] op_sel:[0,1,0]
	v_pk_fma_f32 v[108:109], v[70:71], v[90:91], v[108:109] op_sel:[0,1,0]
	v_pk_mul_f32 v[110:111], v[64:65], v[72:73] op_sel_hi:[1,0]
	v_add_f32_dpp v106, v106, v106 quad_perm:[1,0,3,2] row_mask:0xf bank_mask:0xf bound_ctrl:1
	v_add_f32_dpp v107, v107, v107 quad_perm:[1,0,3,2] row_mask:0xf bank_mask:0xf bound_ctrl:1
	v_pk_fma_f32 v[108:109], v[94:95], v[176:177], v[108:109]
	v_pk_mul_f32 v[112:113], v[66:67], v[72:73] op_sel:[0,1]
	v_add_f32_dpp v106, v106, v106 quad_perm:[2,3,0,1] row_mask:0xf bank_mask:0xf bound_ctrl:1
	v_add_f32_dpp v107, v107, v107 quad_perm:[2,3,0,1] row_mask:0xf bank_mask:0xf bound_ctrl:1
	v_add_f32_dpp v149, v108, v108 row_half_mirror row_mask:0xf bank_mask:0xf bound_ctrl:1
	v_add_f32_dpp v149, v109, v109 row_half_mirror row_mask:0xf bank_mask:0xa
	v_add_f32_dpp v106, v106, v106 row_half_mirror row_mask:0xf bank_mask:0xf bound_ctrl:1
	v_add_f32_dpp v107, v107, v107 row_half_mirror row_mask:0xf bank_mask:0xf bound_ctrl:1
	v_pk_mul_f32 v[144:145], v[68:69], v[74:75] op_sel_hi:[1,0]
	v_pk_mul_f32 v[146:147], v[70:71], v[74:75] op_sel:[0,1]
	v_add_f32_dpp v150, v148, v148 row_ror:8 row_mask:0xf bank_mask:0xf bound_ctrl:1
	v_add_f32_dpp v150, v149, v149 row_ror:8 row_mask:0xf bank_mask:0xc
	v_add_f32_dpp v106, v106, v106 row_mirror row_mask:0xf bank_mask:0xf bound_ctrl:1
	v_add_f32_dpp v107, v107, v107 row_mirror row_mask:0xf bank_mask:0xf bound_ctrl:1
	v_pk_fma_f32 v[110:111], v[92:93], v[84:85], v[110:111] op_sel_hi:[1,0,1]
	v_pk_fma_f32 v[112:113], v[92:93], v[84:85], v[112:113] op_sel:[0,1,0]
	v_pk_fma_f32 v[144:145], v[92:93], v[86:87], v[144:145] op_sel_hi:[1,0,1]
	v_pk_fma_f32 v[146:147], v[92:93], v[86:87], v[146:147] op_sel:[0,1,0]
	v_add_f32_dpp v150, v150, v150 quad_perm:[1,0,3,2] row_mask:0xf bank_mask:0xf bound_ctrl:1
	v_pk_fma_f32 v[64:65], v[106:107], v[80:81], v[110:111] op_sel_hi:[1,0,1]
	v_pk_fma_f32 v[66:67], v[106:107], v[80:81], v[112:113] op_sel:[0,1,0]
	v_add_f32_dpp v150, v150, v150 quad_perm:[2,3,0,1] row_mask:0xf bank_mask:0xf bound_ctrl:1
	v_pk_fma_f32 v[68:69], v[106:107], v[82:83], v[144:145] op_sel_hi:[1,0,1]
	v_pk_fma_f32 v[70:71], v[106:107], v[82:83], v[146:147] op_sel:[0,1,0]
	s_mov_b64 exec, s[34:35]
	ds_write_b32 v178, v150 offset:256
	s_mov_b64 exec, -1
	s_waitcnt lgkmcnt(1)
; #define SC_GET(X, t) do { const float* p = rec + (t) * 320; w##X = *(const f32x4*)p; a##X = *(const f32x4*)(p + 4); b##X = *(const f32x4*)(p + 8); k##X = *(const f32x4*)(p + 12); q##X = *(const f32x4*)(p + 16); \
;                 v##X = *(const f32x4*)(VVa + (t) * 64); } while (0)
; DI void scan_phase(unsigned char* lds, const Ctx& a, const Op& d, const int variant) {
;     ...
;                 SC_GET(A, 0);
; #pragma unroll 2
;                 for (int t = 0; t < SC_T; t += 2) {
;                     SC_GET(B, t + 1);
;                     SC_STEP(A, t);
;                     if (t + 2 < SC_T) SC_GET(A, t + 2);
;                     SC_STEP(B, t + 1);
;                 }
	v_pk_mul_f32 v[106:107], v[64:65], v[44:45] op_sel_hi:[1,0]
	ds_read_b128 v[72:75], v175 offset:6400
	v_pk_mul_f32 v[108:109], v[64:65], v[56:57] op_sel_hi:[1,0]
	ds_read_b128 v[76:79], v175 offset:6416
	v_pk_fma_f32 v[106:107], v[66:67], v[44:45], v[106:107] op_sel:[0,1,0]
	ds_read_b128 v[80:83], v175 offset:6432
	v_pk_fma_f32 v[108:109], v[66:67], v[56:57], v[108:109] op_sel:[0,1,0]
	ds_read_b128 v[84:87], v175 offset:6448
	v_pk_fma_f32 v[106:107], v[68:69], v[46:47], v[106:107] op_sel_hi:[1,0,1]
	ds_read_b128 v[88:91], v175 offset:6464
	v_pk_fma_f32 v[108:109], v[68:69], v[58:59], v[108:109] op_sel_hi:[1,0,1]
	ds_read_b128 v[92:95], v123 offset:42240
	v_pk_fma_f32 v[106:107], v[70:71], v[46:47], v[106:107] op_sel:[0,1,0]
	v_pk_fma_f32 v[108:109], v[70:71], v[58:59], v[108:109] op_sel:[0,1,0]
	v_pk_mul_f32 v[110:111], v[64:65], v[40:41] op_sel_hi:[1,0]
	v_add_f32_dpp v106, v106, v106 quad_perm:[1,0,3,2] row_mask:0xf bank_mask:0xf bound_ctrl:1
	v_add_f32_dpp v107, v107, v107 quad_perm:[1,0,3,2] row_mask:0xf bank_mask:0xf bound_ctrl:1
	v_pk_fma_f32 v[108:109], v[62:63], v[176:177], v[108:109]
	v_pk_mul_f32 v[112:113], v[66:67], v[40:41] op_sel:[0,1]
	v_add_f32_dpp v106, v106, v106 quad_perm:[2,3,0,1] row_mask:0xf bank_mask:0xf bound_ctrl:1
	v_add_f32_dpp v107, v107, v107 quad_perm:[2,3,0,1] row_mask:0xf bank_mask:0xf bound_ctrl:1
	v_add_f32_dpp v148, v108, v108 row_half_mirror row_mask:0xf bank_mask:0xf bound_ctrl:1
	v_add_f32_dpp v148, v109, v109 row_half_mirror row_mask:0xf bank_mask:0xa
	v_add_f32_dpp v106, v106, v106 row_half_mirror row_mask:0xf bank_mask:0xf bound_ctrl:1
	v_add_f32_dpp v107, v107, v107 row_half_mirror row_mask:0xf bank_mask:0xf bound_ctrl:1
	v_pk_mul_f32 v[144:145], v[68:69], v[42:43] op_sel_hi:[1,0]
	v_pk_mul_f32 v[146:147], v[70:71], v[42:43] op_sel:[0,1]
	v_add_f32_dpp v106, v106, v106 row_mirror row_mask:0xf bank_mask:0xf bound_ctrl:1
	v_add_f32_dpp v107, v107, v107 row_mirror row_mask:0xf bank_mask:0xf bound_ctrl:1
	v_pk_fma_f32 v[110:111], v[60:61], v[52:53], v[110:111] op_sel_hi:[1,0,1]
	v_pk_fma_f32 v[112:113], v[60:61], v[52:53], v[112:113] op_sel:[0,1,0]
	v_pk_fma_f32 v[144:145], v[60:61], v[54:55], v[144:145] op_sel_hi:[1,0,1]
	v_pk_fma_f32 v[146:147], v[60:61], v[54:55], v[146:147] op_sel:[0,1,0]
	v_pk_fma_f32 v[64:65], v[106:107], v[48:49], v[110:111] op_sel_hi:[1,0,1]
	v_pk_fma_f32 v[66:67], v[106:107], v[48:49], v[112:113] op_sel:[0,1,0]
	v_pk_fma_f32 v[68:69], v[106:107], v[50:51], v[144:145] op_sel_hi:[1,0,1]
	v_pk_fma_f32 v[70:71], v[106:107], v[50:51], v[146:147] op_sel:[0,1,0]
	s_waitcnt lgkmcnt(0)
	v_pk_mul_f32 v[106:107], v[64:65], v[76:77] op_sel_hi:[1,0]
	ds_read_b128 v[40:43], v175 offset:7680
	v_pk_mul_f32 v[108:109], v[64:65], v[88:89] op_sel_hi:[1,0]
	ds_read_b128 v[44:47], v175 offset:7696
	v_pk_fma_f32 v[106:107], v[66:67], v[76:77], v[106:107] op_sel:[0,1,0]
	ds_read_b128 v[48:51], v175 offset:7712
	v_pk_fma_f32 v[108:109], v[66:67], v[88:89], v[108:109] op_sel:[0,1,0]
	ds_read_b128 v[52:55], v175 offset:7728
	v_pk_fma_f32 v[106:107], v[68:69], v[78:79], v[106:107] op_sel_hi:[1,0,1]
	ds_read_b128 v[56:59], v175 offset:7744
	v_pk_fma_f32 v[108:109], v[68:69], v[90:91], v[108:109] op_sel_hi:[1,0,1]
	ds_read_b128 v[60:63], v123 offset:42496
	v_pk_fma_f32 v[106:107], v[70:71], v[78:79], v[106:107] op_sel:[0,1,0]
	v_pk_fma_f32 v[108:109], v[70:71], v[90:91], v[108:109] op_sel:[0,1,0]
	v_pk_mul_f32 v[110:111], v[64:65], v[72:73] op_sel_hi:[1,0]
	v_add_f32_dpp v106, v106, v106 quad_perm:[1,0,3,2] row_mask:0xf bank_mask:0xf bound_ctrl:1
	v_add_f32_dpp v107, v107, v107 quad_perm:[1,0,3,2] row_mask:0xf bank_mask:0xf bound_ctrl:1
	v_pk_fma_f32 v[108:109], v[94:95], v[176:177], v[108:109]
	v_pk_mul_f32 v[112:113], v[66:67], v[72:73] op_sel:[0,1]
	v_add_f32_dpp v106, v106, v106 quad_perm:[2,3,0,1] row_mask:0xf bank_mask:0xf bound_ctrl:1
	v_add_f32_dpp v107, v107, v107 quad_perm:[2,3,0,1] row_mask:0xf bank_mask:0xf bound_ctrl:1
	v_add_f32_dpp v149, v108, v108 row_half_mirror row_mask:0xf bank_mask:0xf bound_ctrl:1
	v_add_f32_dpp v149, v109, v109 row_half_mirror row_mask:0xf bank_mask:0xa
	v_add_f32_dpp v106, v106, v106 row_half_mirror row_mask:0xf bank_mask:0xf bound_ctrl:1
	v_add_f32_dpp v107, v107, v107 row_half_mirror row_mask:0xf bank_mask:0xf bound_ctrl:1
	v_pk_mul_f32 v[144:145], v[68:69], v[74:75] op_sel_hi:[1,0]
	v_pk_mul_f32 v[146:147], v[70:71], v[74:75] op_sel:[0,1]
	v_add_f32_dpp v150, v148, v148 row_ror:8 row_mask:0xf bank_mask:0xf bound_ctrl:1
	v_add_f32_dpp v150, v149, v149 row_ror:8 row_mask:0xf bank_mask:0xc
	v_add_f32_dpp v106, v106, v106 row_mirror row_mask:0xf bank_mask:0xf bound_ctrl:1
	v_add_f32_dpp v107, v107, v107 row_mirror row_mask:0xf bank_mask:0xf bound_ctrl:1
	v_pk_fma_f32 v[110:111], v[92:93], v[84:85], v[110:111] op_sel_hi:[1,0,1]
	v_pk_fma_f32 v[112:113], v[92:93], v[84:85], v[112:113] op_sel:[0,1,0]
	v_pk_fma_f32 v[144:145], v[92:93], v[86:87], v[144:145] op_sel_hi:[1,0,1]
	v_pk_fma_f32 v[146:147], v[92:93], v[86:87], v[146:147] op_sel:[0,1,0]
	v_add_f32_dpp v150, v150, v150 quad_perm:[1,0,3,2] row_mask:0xf bank_mask:0xf bound_ctrl:1
	v_pk_fma_f32 v[64:65], v[106:107], v[80:81], v[110:111] op_sel_hi:[1,0,1]
	v_pk_fma_f32 v[66:67], v[106:107], v[80:81], v[112:113] op_sel:[0,1,0]
	v_add_f32_dpp v150, v150, v150 quad_perm:[2,3,0,1] row_mask:0xf bank_mask:0xf bound_ctrl:1
	v_pk_fma_f32 v[68:69], v[106:107], v[82:83], v[144:145] op_sel_hi:[1,0,1]
	v_pk_fma_f32 v[70:71], v[106:107], v[82:83], v[146:147] op_sel:[0,1,0]
	s_mov_b64 exec, s[34:35]
	ds_write_b32 v178, v150 offset:512
	s_mov_b64 exec, -1
	s_waitcnt lgkmcnt(1)
; #define SC_GET(X, t) do { const float* p = rec + (t) * 320; w##X = *(const f32x4*)p; a##X = *(const f32x4*)(p + 4); b##X = *(const f32x4*)(p + 8); k##X = *(const f32x4*)(p + 12); q##X = *(const f32x4*)(p + 16); \
;                 v##X = *(const f32x4*)(VVa + (t) * 64); } while (0)
; DI void scan_phase(unsigned char* lds, const Ctx& a, const Op& d, const int variant) {
;     ...
;                 SC_GET(A, 0);
; #pragma unroll 2
;                 for (int t = 0; t < SC_T; t += 2) {
;                     SC_GET(B, t + 1);
;                     SC_STEP(A, t);
;                     if (t + 2 < SC_T) SC_GET(A, t + 2);
;                     SC_STEP(B, t + 1);
;                 }
	v_pk_mul_f32 v[106:107], v[64:65], v[44:45] op_sel_hi:[1,0]
	ds_read_b128 v[72:75], v175 offset:8960
	v_pk_mul_f32 v[108:109], v[64:65], v[56:57] op_sel_hi:[1,0]
	ds_read_b128 v[76:79], v175 offset:8976
	v_pk_fma_f32 v[106:107], v[66:67], v[44:45], v[106:107] op_sel:[0,1,0]
	ds_read_b128 v[80:83], v175 offset:8992
	v_pk_fma_f32 v[108:109], v[66:67], v[56:57], v[108:109] op_sel:[0,1,0]
	ds_read_b128 v[84:87], v175 offset:9008
	v_pk_fma_f32 v[106:107], v[68:69], v[46:47], v[106:107] op_sel_hi:[1,0,1]
	ds_read_b128 v[88:91], v175 offset:9024
	v_pk_fma_f32 v[108:109], v[68:69], v[58:59], v[108:109] op_sel_hi:[1,0,1]
	ds_read_b128 v[92:95], v123 offset:42752
	v_pk_fma_f32 v[106:107], v[70:71], v[46:47], v[106:107] op_sel:[0,1,0]
	v_pk_fma_f32 v[108:109], v[70:71], v[58:59], v[108:109] op_sel:[0,1,0]
	v_pk_mul_f32 v[110:111], v[64:65], v[40:41] op_sel_hi:[1,0]
	v_add_f32_dpp v106, v106, v106 quad_perm:[1,0,3,2] row_mask:0xf bank_mask:0xf bound_ctrl:1
	v_add_f32_dpp v107, v107, v107 quad_perm:[1,0,3,2] row_mask:0xf bank_mask:0xf bound_ctrl:1
	v_pk_fma_f32 v[108:109], v[62:63], v[176:177], v[108:109]
	v_pk_mul_f32 v[112:113], v[66:67], v[40:41] op_sel:[0,1]
	v_add_f32_dpp v106, v106, v106 quad_perm:[2,3,0,1] row_mask:0xf bank_mask:0xf bound_ctrl:1
	v_add_f32_dpp v107, v107, v107 quad_perm:[2,3,0,1] row_mask:0xf bank_mask:0xf bound_ctrl:1
	v_add_f32_dpp v148, v108, v108 row_half_mirror row_mask:0xf bank_mask:0xf bound_ctrl:1
	v_add_f32_dpp v148, v109, v109 row_half_mirror row_mask:0xf bank_mask:0xa
	v_add_f32_dpp v106, v106, v106 row_half_mirror row_mask:0xf bank_mask:0xf bound_ctrl:1
	v_add_f32_dpp v107, v107, v107 row_half_mirror row_mask:0xf bank_mask:0xf bound_ctrl:1
	v_pk_mul_f32 v[144:145], v[68:69], v[42:43] op_sel_hi:[1,0]
	v_pk_mul_f32 v[146:147], v[70:71], v[42:43] op_sel:[0,1]
	v_add_f32_dpp v106, v106, v106 row_mirror row_mask:0xf bank_mask:0xf bound_ctrl:1
	v_add_f32_dpp v107, v107, v107 row_mirror row_mask:0xf bank_mask:0xf bound_ctrl:1
	v_pk_fma_f32 v[110:111], v[60:61], v[52:53], v[110:111] op_sel_hi:[1,0,1]
	v_pk_fma_f32 v[112:113], v[60:61], v[52:53], v[112:113] op_sel:[0,1,0]
	v_pk_fma_f32 v[144:145], v[60:61], v[54:55], v[144:145] op_sel_hi:[1,0,1]
	v_pk_fma_f32 v[146:147], v[60:61], v[54:55], v[146:147] op_sel:[0,1,0]
	v_pk_fma_f32 v[64:65], v[106:107], v[48:49], v[110:111] op_sel_hi:[1,0,1]
	v_pk_fma_f32 v[66:67], v[106:107], v[48:49], v[112:113] op_sel:[0,1,0]
	v_pk_fma_f32 v[68:69], v[106:107], v[50:51], v[144:145] op_sel_hi:[1,0,1]
	v_pk_fma_f32 v[70:71], v[106:107], v[50:51], v[146:147] op_sel:[0,1,0]
	s_waitcnt lgkmcnt(0)
	v_pk_mul_f32 v[106:107], v[64:65], v[76:77] op_sel_hi:[1,0]
	ds_read_b128 v[40:43], v175 offset:10240
	v_pk_mul_f32 v[108:109], v[64:65], v[88:89] op_sel_hi:[1,0]
	ds_read_b128 v[44:47], v175 offset:10256
	v_pk_fma_f32 v[106:107], v[66:67], v[76:77], v[106:107] op_sel:[0,1,0]
	ds_read_b128 v[48:51], v175 offset:10272
	v_pk_fma_f32 v[108:109], v[66:67], v[88:89], v[108:109] op_sel:[0,1,0]
	ds_read_b128 v[52:55], v175 offset:10288
	v_pk_fma_f32 v[106:107], v[68:69], v[78:79], v[106:107] op_sel_hi:[1,0,1]
	ds_read_b128 v[56:59], v175 offset:10304
	v_pk_fma_f32 v[108:109], v[68:69], v[90:91], v[108:109] op_sel_hi:[1,0,1]
	ds_read_b128 v[60:63], v123 offset:43008
	v_pk_fma_f32 v[106:107], v[70:71], v[78:79], v[106:107] op_sel:[0,1,0]
	v_pk_fma_f32 v[108:109], v[70:71], v[90:91], v[108:109] op_sel:[0,1,0]
	v_pk_mul_f32 v[110:111], v[64:65], v[72:73] op_sel_hi:[1,0]
	v_add_f32_dpp v106, v106, v106 quad_perm:[1,0,3,2] row_mask:0xf bank_mask:0xf bound_ctrl:1
	v_add_f32_dpp v107, v107, v107 quad_perm:[1,0,3,2] row_mask:0xf bank_mask:0xf bound_ctrl:1
	v_pk_fma_f32 v[108:109], v[94:95], v[176:177], v[108:109]
	v_pk_mul_f32 v[112:113], v[66:67], v[72:73] op_sel:[0,1]
	v_add_f32_dpp v106, v106, v106 quad_perm:[2,3,0,1] row_mask:0xf bank_mask:0xf bound_ctrl:1
	v_add_f32_dpp v107, v107, v107 quad_perm:[2,3,0,1] row_mask:0xf bank_mask:0xf bound_ctrl:1
	v_add_f32_dpp v149, v108, v108 row_half_mirror row_mask:0xf bank_mask:0xf bound_ctrl:1
	v_add_f32_dpp v149, v109, v109 row_half_mirror row_mask:0xf bank_mask:0xa
	v_add_f32_dpp v106, v106, v106 row_half_mirror row_mask:0xf bank_mask:0xf bound_ctrl:1
	v_add_f32_dpp v107, v107, v107 row_half_mirror row_mask:0xf bank_mask:0xf bound_ctrl:1
	v_pk_mul_f32 v[144:145], v[68:69], v[74:75] op_sel_hi:[1,0]
	v_pk_mul_f32 v[146:147], v[70:71], v[74:75] op_sel:[0,1]
	v_add_f32_dpp v150, v148, v148 row_ror:8 row_mask:0xf bank_mask:0xf bound_ctrl:1
	v_add_f32_dpp v150, v149, v149 row_ror:8 row_mask:0xf bank_mask:0xc
	v_add_f32_dpp v106, v106, v106 row_mirror row_mask:0xf bank_mask:0xf bound_ctrl:1
	v_add_f32_dpp v107, v107, v107 row_mirror row_mask:0xf bank_mask:0xf bound_ctrl:1
	v_pk_fma_f32 v[110:111], v[92:93], v[84:85], v[110:111] op_sel_hi:[1,0,1]
	v_pk_fma_f32 v[112:113], v[92:93], v[84:85], v[112:113] op_sel:[0,1,0]
	v_pk_fma_f32 v[144:145], v[92:93], v[86:87], v[144:145] op_sel_hi:[1,0,1]
	v_pk_fma_f32 v[146:147], v[92:93], v[86:87], v[146:147] op_sel:[0,1,0]
	v_add_f32_dpp v150, v150, v150 quad_perm:[1,0,3,2] row_mask:0xf bank_mask:0xf bound_ctrl:1
	v_pk_fma_f32 v[64:65], v[106:107], v[80:81], v[110:111] op_sel_hi:[1,0,1]
	v_pk_fma_f32 v[66:67], v[106:107], v[80:81], v[112:113] op_sel:[0,1,0]
	v_add_f32_dpp v150, v150, v150 quad_perm:[2,3,0,1] row_mask:0xf bank_mask:0xf bound_ctrl:1
	v_pk_fma_f32 v[68:69], v[106:107], v[82:83], v[144:145] op_sel_hi:[1,0,1]
	v_pk_fma_f32 v[70:71], v[106:107], v[82:83], v[146:147] op_sel:[0,1,0]
	s_mov_b64 exec, s[34:35]
	ds_write_b32 v178, v150 offset:768
	s_mov_b64 exec, -1
	s_waitcnt lgkmcnt(1)
; #define SC_GET(X, t) do { const float* p = rec + (t) * 320; w##X = *(const f32x4*)p; a##X = *(const f32x4*)(p + 4); b##X = *(const f32x4*)(p + 8); k##X = *(const f32x4*)(p + 12); q##X = *(const f32x4*)(p + 16); \
;                 v##X = *(const f32x4*)(VVa + (t) * 64); } while (0)
; DI void scan_phase(unsigned char* lds, const Ctx& a, const Op& d, const int variant) {
;     ...
;                 SC_GET(A, 0);
; #pragma unroll 2
;                 for (int t = 0; t < SC_T; t += 2) {
;                     SC_GET(B, t + 1);
;                     SC_STEP(A, t);
;                     if (t + 2 < SC_T) SC_GET(A, t + 2);
;                     SC_STEP(B, t + 1);
;                 }
	v_pk_mul_f32 v[106:107], v[64:65], v[44:45] op_sel_hi:[1,0]
	ds_read_b128 v[72:75], v175 offset:11520
	v_pk_mul_f32 v[108:109], v[64:65], v[56:57] op_sel_hi:[1,0]
	ds_read_b128 v[76:79], v175 offset:11536
	v_pk_fma_f32 v[106:107], v[66:67], v[44:45], v[106:107] op_sel:[0,1,0]
	ds_read_b128 v[80:83], v175 offset:11552
	v_pk_fma_f32 v[108:109], v[66:67], v[56:57], v[108:109] op_sel:[0,1,0]
	ds_read_b128 v[84:87], v175 offset:11568
	v_pk_fma_f32 v[106:107], v[68:69], v[46:47], v[106:107] op_sel_hi:[1,0,1]
	ds_read_b128 v[88:91], v175 offset:11584
	v_pk_fma_f32 v[108:109], v[68:69], v[58:59], v[108:109] op_sel_hi:[1,0,1]
	ds_read_b128 v[92:95], v123 offset:43264
	v_pk_fma_f32 v[106:107], v[70:71], v[46:47], v[106:107] op_sel:[0,1,0]
	v_pk_fma_f32 v[108:109], v[70:71], v[58:59], v[108:109] op_sel:[0,1,0]
	v_pk_mul_f32 v[110:111], v[64:65], v[40:41] op_sel_hi:[1,0]
	v_add_f32_dpp v106, v106, v106 quad_perm:[1,0,3,2] row_mask:0xf bank_mask:0xf bound_ctrl:1
	v_add_f32_dpp v107, v107, v107 quad_perm:[1,0,3,2] row_mask:0xf bank_mask:0xf bound_ctrl:1
	v_pk_fma_f32 v[108:109], v[62:63], v[176:177], v[108:109]
	v_pk_mul_f32 v[112:113], v[66:67], v[40:41] op_sel:[0,1]
	v_add_f32_dpp v106, v106, v106 quad_perm:[2,3,0,1] row_mask:0xf bank_mask:0xf bound_ctrl:1
	v_add_f32_dpp v107, v107, v107 quad_perm:[2,3,0,1] row_mask:0xf bank_mask:0xf bound_ctrl:1
	v_add_f32_dpp v148, v108, v108 row_half_mirror row_mask:0xf bank_mask:0xf bound_ctrl:1
	v_add_f32_dpp v148, v109, v109 row_half_mirror row_mask:0xf bank_mask:0xa
	v_add_f32_dpp v106, v106, v106 row_half_mirror row_mask:0xf bank_mask:0xf bound_ctrl:1
	v_add_f32_dpp v107, v107, v107 row_half_mirror row_mask:0xf bank_mask:0xf bound_ctrl:1
	v_pk_mul_f32 v[144:145], v[68:69], v[42:43] op_sel_hi:[1,0]
	v_pk_mul_f32 v[146:147], v[70:71], v[42:43] op_sel:[0,1]
	v_add_f32_dpp v106, v106, v106 row_mirror row_mask:0xf bank_mask:0xf bound_ctrl:1
	v_add_f32_dpp v107, v107, v107 row_mirror row_mask:0xf bank_mask:0xf bound_ctrl:1
	v_pk_fma_f32 v[110:111], v[60:61], v[52:53], v[110:111] op_sel_hi:[1,0,1]
	v_pk_fma_f32 v[112:113], v[60:61], v[52:53], v[112:113] op_sel:[0,1,0]
	v_pk_fma_f32 v[144:145], v[60:61], v[54:55], v[144:145] op_sel_hi:[1,0,1]
	v_pk_fma_f32 v[146:147], v[60:61], v[54:55], v[146:147] op_sel:[0,1,0]
	v_pk_fma_f32 v[64:65], v[106:107], v[48:49], v[110:111] op_sel_hi:[1,0,1]
	v_pk_fma_f32 v[66:67], v[106:107], v[48:49], v[112:113] op_sel:[0,1,0]
	v_pk_fma_f32 v[68:69], v[106:107], v[50:51], v[144:145] op_sel_hi:[1,0,1]
	v_pk_fma_f32 v[70:71], v[106:107], v[50:51], v[146:147] op_sel:[0,1,0]
	s_waitcnt lgkmcnt(0)
	v_pk_mul_f32 v[106:107], v[64:65], v[76:77] op_sel_hi:[1,0]
	ds_read_b128 v[40:43], v175 offset:12800
	v_pk_mul_f32 v[108:109], v[64:65], v[88:89] op_sel_hi:[1,0]
	ds_read_b128 v[44:47], v175 offset:12816
	v_pk_fma_f32 v[106:107], v[66:67], v[76:77], v[106:107] op_sel:[0,1,0]
	ds_read_b128 v[48:51], v175 offset:12832
	v_pk_fma_f32 v[108:109], v[66:67], v[88:89], v[108:109] op_sel:[0,1,0]
	ds_read_b128 v[52:55], v175 offset:12848
	v_pk_fma_f32 v[106:107], v[68:69], v[78:79], v[106:107] op_sel_hi:[1,0,1]
	ds_read_b128 v[56:59], v175 offset:12864
	v_pk_fma_f32 v[108:109], v[68:69], v[90:91], v[108:109] op_sel_hi:[1,0,1]
	ds_read_b128 v[60:63], v123 offset:43520
	v_pk_fma_f32 v[106:107], v[70:71], v[78:79], v[106:107] op_sel:[0,1,0]
	v_pk_fma_f32 v[108:109], v[70:71], v[90:91], v[108:109] op_sel:[0,1,0]
	v_pk_mul_f32 v[110:111], v[64:65], v[72:73] op_sel_hi:[1,0]
	v_add_f32_dpp v106, v106, v106 quad_perm:[1,0,3,2] row_mask:0xf bank_mask:0xf bound_ctrl:1
	v_add_f32_dpp v107, v107, v107 quad_perm:[1,0,3,2] row_mask:0xf bank_mask:0xf bound_ctrl:1
	v_pk_fma_f32 v[108:109], v[94:95], v[176:177], v[108:109]
	v_pk_mul_f32 v[112:113], v[66:67], v[72:73] op_sel:[0,1]
	v_add_f32_dpp v106, v106, v106 quad_perm:[2,3,0,1] row_mask:0xf bank_mask:0xf bound_ctrl:1
	v_add_f32_dpp v107, v107, v107 quad_perm:[2,3,0,1] row_mask:0xf bank_mask:0xf bound_ctrl:1
	v_add_f32_dpp v149, v108, v108 row_half_mirror row_mask:0xf bank_mask:0xf bound_ctrl:1
	v_add_f32_dpp v149, v109, v109 row_half_mirror row_mask:0xf bank_mask:0xa
	v_add_f32_dpp v106, v106, v106 row_half_mirror row_mask:0xf bank_mask:0xf bound_ctrl:1
	v_add_f32_dpp v107, v107, v107 row_half_mirror row_mask:0xf bank_mask:0xf bound_ctrl:1
	v_pk_mul_f32 v[144:145], v[68:69], v[74:75] op_sel_hi:[1,0]
	v_pk_mul_f32 v[146:147], v[70:71], v[74:75] op_sel:[0,1]
	v_add_f32_dpp v150, v148, v148 row_ror:8 row_mask:0xf bank_mask:0xf bound_ctrl:1
	v_add_f32_dpp v150, v149, v149 row_ror:8 row_mask:0xf bank_mask:0xc
	v_add_f32_dpp v106, v106, v106 row_mirror row_mask:0xf bank_mask:0xf bound_ctrl:1
	v_add_f32_dpp v107, v107, v107 row_mirror row_mask:0xf bank_mask:0xf bound_ctrl:1
	v_pk_fma_f32 v[110:111], v[92:93], v[84:85], v[110:111] op_sel_hi:[1,0,1]
	v_pk_fma_f32 v[112:113], v[92:93], v[84:85], v[112:113] op_sel:[0,1,0]
	v_pk_fma_f32 v[144:145], v[92:93], v[86:87], v[144:145] op_sel_hi:[1,0,1]
	v_pk_fma_f32 v[146:147], v[92:93], v[86:87], v[146:147] op_sel:[0,1,0]
	v_add_f32_dpp v150, v150, v150 quad_perm:[1,0,3,2] row_mask:0xf bank_mask:0xf bound_ctrl:1
	v_pk_fma_f32 v[64:65], v[106:107], v[80:81], v[110:111] op_sel_hi:[1,0,1]
	v_pk_fma_f32 v[66:67], v[106:107], v[80:81], v[112:113] op_sel:[0,1,0]
	v_add_f32_dpp v150, v150, v150 quad_perm:[2,3,0,1] row_mask:0xf bank_mask:0xf bound_ctrl:1
	v_pk_fma_f32 v[68:69], v[106:107], v[82:83], v[144:145] op_sel_hi:[1,0,1]
	v_pk_fma_f32 v[70:71], v[106:107], v[82:83], v[146:147] op_sel:[0,1,0]
	s_mov_b64 exec, s[34:35]
	ds_write_b32 v178, v150 offset:1024
	s_mov_b64 exec, -1
	s_waitcnt lgkmcnt(1)
; #define SC_GET(X, t) do { const float* p = rec + (t) * 320; w##X = *(const f32x4*)p; a##X = *(const f32x4*)(p + 4); b##X = *(const f32x4*)(p + 8); k##X = *(const f32x4*)(p + 12); q##X = *(const f32x4*)(p + 16); \
;                 v##X = *(const f32x4*)(VVa + (t) * 64); } while (0)
; DI void scan_phase(unsigned char* lds, const Ctx& a, const Op& d, const int variant) {
;     ...
;                 SC_GET(A, 0);
; #pragma unroll 2
;                 for (int t = 0; t < SC_T; t += 2) {
;                     SC_GET(B, t + 1);
;                     SC_STEP(A, t);
;                     if (t + 2 < SC_T) SC_GET(A, t + 2);
;                     SC_STEP(B, t + 1);
;                 }
	v_pk_mul_f32 v[106:107], v[64:65], v[44:45] op_sel_hi:[1,0]
	ds_read_b128 v[72:75], v175 offset:14080
	v_pk_mul_f32 v[108:109], v[64:65], v[56:57] op_sel_hi:[1,0]
	ds_read_b128 v[76:79], v175 offset:14096
	v_pk_fma_f32 v[106:107], v[66:67], v[44:45], v[106:107] op_sel:[0,1,0]
	ds_read_b128 v[80:83], v175 offset:14112
	v_pk_fma_f32 v[108:109], v[66:67], v[56:57], v[108:109] op_sel:[0,1,0]
	ds_read_b128 v[84:87], v175 offset:14128
	v_pk_fma_f32 v[106:107], v[68:69], v[46:47], v[106:107] op_sel_hi:[1,0,1]
	ds_read_b128 v[88:91], v175 offset:14144
	v_pk_fma_f32 v[108:109], v[68:69], v[58:59], v[108:109] op_sel_hi:[1,0,1]
	ds_read_b128 v[92:95], v123 offset:43776
	v_pk_fma_f32 v[106:107], v[70:71], v[46:47], v[106:107] op_sel:[0,1,0]
	v_pk_fma_f32 v[108:109], v[70:71], v[58:59], v[108:109] op_sel:[0,1,0]
	v_pk_mul_f32 v[110:111], v[64:65], v[40:41] op_sel_hi:[1,0]
	v_add_f32_dpp v106, v106, v106 quad_perm:[1,0,3,2] row_mask:0xf bank_mask:0xf bound_ctrl:1
	v_add_f32_dpp v107, v107, v107 quad_perm:[1,0,3,2] row_mask:0xf bank_mask:0xf bound_ctrl:1
	v_pk_fma_f32 v[108:109], v[62:63], v[176:177], v[108:109]
	v_pk_mul_f32 v[112:113], v[66:67], v[40:41] op_sel:[0,1]
	v_add_f32_dpp v106, v106, v106 quad_perm:[2,3,0,1] row_mask:0xf bank_mask:0xf bound_ctrl:1
	v_add_f32_dpp v107, v107, v107 quad_perm:[2,3,0,1] row_mask:0xf bank_mask:0xf bound_ctrl:1
	v_add_f32_dpp v148, v108, v108 row_half_mirror row_mask:0xf bank_mask:0xf bound_ctrl:1
	v_add_f32_dpp v148, v109, v109 row_half_mirror row_mask:0xf bank_mask:0xa
	v_add_f32_dpp v106, v106, v106 row_half_mirror row_mask:0xf bank_mask:0xf bound_ctrl:1
	v_add_f32_dpp v107, v107, v107 row_half_mirror row_mask:0xf bank_mask:0xf bound_ctrl:1
	v_pk_mul_f32 v[144:145], v[68:69], v[42:43] op_sel_hi:[1,0]
	v_pk_mul_f32 v[146:147], v[70:71], v[42:43] op_sel:[0,1]
	v_add_f32_dpp v106, v106, v106 row_mirror row_mask:0xf bank_mask:0xf bound_ctrl:1
	v_add_f32_dpp v107, v107, v107 row_mirror row_mask:0xf bank_mask:0xf bound_ctrl:1
	v_pk_fma_f32 v[110:111], v[60:61], v[52:53], v[110:111] op_sel_hi:[1,0,1]
	v_pk_fma_f32 v[112:113], v[60:61], v[52:53], v[112:113] op_sel:[0,1,0]
	v_pk_fma_f32 v[144:145], v[60:61], v[54:55], v[144:145] op_sel_hi:[1,0,1]
	v_pk_fma_f32 v[146:147], v[60:61], v[54:55], v[146:147] op_sel:[0,1,0]
	v_pk_fma_f32 v[64:65], v[106:107], v[48:49], v[110:111] op_sel_hi:[1,0,1]
	v_pk_fma_f32 v[66:67], v[106:107], v[48:49], v[112:113] op_sel:[0,1,0]
	v_pk_fma_f32 v[68:69], v[106:107], v[50:51], v[144:145] op_sel_hi:[1,0,1]
	v_pk_fma_f32 v[70:71], v[106:107], v[50:51], v[146:147] op_sel:[0,1,0]
	s_waitcnt lgkmcnt(0)
	v_pk_mul_f32 v[106:107], v[64:65], v[76:77] op_sel_hi:[1,0]
	ds_read_b128 v[40:43], v175 offset:15360
	v_pk_mul_f32 v[108:109], v[64:65], v[88:89] op_sel_hi:[1,0]
	ds_read_b128 v[44:47], v175 offset:15376
	v_pk_fma_f32 v[106:107], v[66:67], v[76:77], v[106:107] op_sel:[0,1,0]
	ds_read_b128 v[48:51], v175 offset:15392
	v_pk_fma_f32 v[108:109], v[66:67], v[88:89], v[108:109] op_sel:[0,1,0]
	ds_read_b128 v[52:55], v175 offset:15408
	v_pk_fma_f32 v[106:107], v[68:69], v[78:79], v[106:107] op_sel_hi:[1,0,1]
	ds_read_b128 v[56:59], v175 offset:15424
	v_pk_fma_f32 v[108:109], v[68:69], v[90:91], v[108:109] op_sel_hi:[1,0,1]
	ds_read_b128 v[60:63], v123 offset:44032
	v_pk_fma_f32 v[106:107], v[70:71], v[78:79], v[106:107] op_sel:[0,1,0]
	v_pk_fma_f32 v[108:109], v[70:71], v[90:91], v[108:109] op_sel:[0,1,0]
	v_pk_mul_f32 v[110:111], v[64:65], v[72:73] op_sel_hi:[1,0]
	v_add_f32_dpp v106, v106, v106 quad_perm:[1,0,3,2] row_mask:0xf bank_mask:0xf bound_ctrl:1
	v_add_f32_dpp v107, v107, v107 quad_perm:[1,0,3,2] row_mask:0xf bank_mask:0xf bound_ctrl:1
	v_pk_fma_f32 v[108:109], v[94:95], v[176:177], v[108:109]
	v_pk_mul_f32 v[112:113], v[66:67], v[72:73] op_sel:[0,1]
	v_add_f32_dpp v106, v106, v106 quad_perm:[2,3,0,1] row_mask:0xf bank_mask:0xf bound_ctrl:1
	v_add_f32_dpp v107, v107, v107 quad_perm:[2,3,0,1] row_mask:0xf bank_mask:0xf bound_ctrl:1
	v_add_f32_dpp v149, v108, v108 row_half_mirror row_mask:0xf bank_mask:0xf bound_ctrl:1
	v_add_f32_dpp v149, v109, v109 row_half_mirror row_mask:0xf bank_mask:0xa
	v_add_f32_dpp v106, v106, v106 row_half_mirror row_mask:0xf bank_mask:0xf bound_ctrl:1
	v_add_f32_dpp v107, v107, v107 row_half_mirror row_mask:0xf bank_mask:0xf bound_ctrl:1
	v_pk_mul_f32 v[144:145], v[68:69], v[74:75] op_sel_hi:[1,0]
	v_pk_mul_f32 v[146:147], v[70:71], v[74:75] op_sel:[0,1]
	v_add_f32_dpp v150, v148, v148 row_ror:8 row_mask:0xf bank_mask:0xf bound_ctrl:1
	v_add_f32_dpp v150, v149, v149 row_ror:8 row_mask:0xf bank_mask:0xc
	v_add_f32_dpp v106, v106, v106 row_mirror row_mask:0xf bank_mask:0xf bound_ctrl:1
	v_add_f32_dpp v107, v107, v107 row_mirror row_mask:0xf bank_mask:0xf bound_ctrl:1
	v_pk_fma_f32 v[110:111], v[92:93], v[84:85], v[110:111] op_sel_hi:[1,0,1]
	v_pk_fma_f32 v[112:113], v[92:93], v[84:85], v[112:113] op_sel:[0,1,0]
	v_pk_fma_f32 v[144:145], v[92:93], v[86:87], v[144:145] op_sel_hi:[1,0,1]
	v_pk_fma_f32 v[146:147], v[92:93], v[86:87], v[146:147] op_sel:[0,1,0]
	v_add_f32_dpp v150, v150, v150 quad_perm:[1,0,3,2] row_mask:0xf bank_mask:0xf bound_ctrl:1
	v_pk_fma_f32 v[64:65], v[106:107], v[80:81], v[110:111] op_sel_hi:[1,0,1]
	v_pk_fma_f32 v[66:67], v[106:107], v[80:81], v[112:113] op_sel:[0,1,0]
	v_add_f32_dpp v150, v150, v150 quad_perm:[2,3,0,1] row_mask:0xf bank_mask:0xf bound_ctrl:1
	v_pk_fma_f32 v[68:69], v[106:107], v[82:83], v[144:145] op_sel_hi:[1,0,1]
	v_pk_fma_f32 v[70:71], v[106:107], v[82:83], v[146:147] op_sel:[0,1,0]
	s_mov_b64 exec, s[34:35]
	ds_write_b32 v178, v150 offset:1280
	s_mov_b64 exec, -1
	s_waitcnt lgkmcnt(1)
; #define SC_GET(X, t) do { const float* p = rec + (t) * 320; w##X = *(const f32x4*)p; a##X = *(const f32x4*)(p + 4); b##X = *(const f32x4*)(p + 8); k##X = *(const f32x4*)(p + 12); q##X = *(const f32x4*)(p + 16); \
;                 v##X = *(const f32x4*)(VVa + (t) * 64); } while (0)
; DI void scan_phase(unsigned char* lds, const Ctx& a, const Op& d, const int variant) {
;     ...
;                 SC_GET(A, 0);
; #pragma unroll 2
;                 for (int t = 0; t < SC_T; t += 2) {
;                     SC_GET(B, t + 1);
;                     SC_STEP(A, t);
;                     if (t + 2 < SC_T) SC_GET(A, t + 2);
;                     SC_STEP(B, t + 1);
;                 }
	v_pk_mul_f32 v[106:107], v[64:65], v[44:45] op_sel_hi:[1,0]
	ds_read_b128 v[72:75], v175 offset:16640
	v_pk_mul_f32 v[108:109], v[64:65], v[56:57] op_sel_hi:[1,0]
	ds_read_b128 v[76:79], v175 offset:16656
	v_pk_fma_f32 v[106:107], v[66:67], v[44:45], v[106:107] op_sel:[0,1,0]
	ds_read_b128 v[80:83], v175 offset:16672
	v_pk_fma_f32 v[108:109], v[66:67], v[56:57], v[108:109] op_sel:[0,1,0]
	ds_read_b128 v[84:87], v175 offset:16688
	v_pk_fma_f32 v[106:107], v[68:69], v[46:47], v[106:107] op_sel_hi:[1,0,1]
	ds_read_b128 v[88:91], v175 offset:16704
	v_pk_fma_f32 v[108:109], v[68:69], v[58:59], v[108:109] op_sel_hi:[1,0,1]
	ds_read_b128 v[92:95], v123 offset:44288
	v_pk_fma_f32 v[106:107], v[70:71], v[46:47], v[106:107] op_sel:[0,1,0]
	v_pk_fma_f32 v[108:109], v[70:71], v[58:59], v[108:109] op_sel:[0,1,0]
	v_pk_mul_f32 v[110:111], v[64:65], v[40:41] op_sel_hi:[1,0]
	v_add_f32_dpp v106, v106, v106 quad_perm:[1,0,3,2] row_mask:0xf bank_mask:0xf bound_ctrl:1
	v_add_f32_dpp v107, v107, v107 quad_perm:[1,0,3,2] row_mask:0xf bank_mask:0xf bound_ctrl:1
	v_pk_fma_f32 v[108:109], v[62:63], v[176:177], v[108:109]
	v_pk_mul_f32 v[112:113], v[66:67], v[40:41] op_sel:[0,1]
	v_add_f32_dpp v106, v106, v106 quad_perm:[2,3,0,1] row_mask:0xf bank_mask:0xf bound_ctrl:1
	v_add_f32_dpp v107, v107, v107 quad_perm:[2,3,0,1] row_mask:0xf bank_mask:0xf bound_ctrl:1
	v_add_f32_dpp v148, v108, v108 row_half_mirror row_mask:0xf bank_mask:0xf bound_ctrl:1
	v_add_f32_dpp v148, v109, v109 row_half_mirror row_mask:0xf bank_mask:0xa
	v_add_f32_dpp v106, v106, v106 row_half_mirror row_mask:0xf bank_mask:0xf bound_ctrl:1
	v_add_f32_dpp v107, v107, v107 row_half_mirror row_mask:0xf bank_mask:0xf bound_ctrl:1
	v_pk_mul_f32 v[144:145], v[68:69], v[42:43] op_sel_hi:[1,0]
	v_pk_mul_f32 v[146:147], v[70:71], v[42:43] op_sel:[0,1]
	v_add_f32_dpp v106, v106, v106 row_mirror row_mask:0xf bank_mask:0xf bound_ctrl:1
	v_add_f32_dpp v107, v107, v107 row_mirror row_mask:0xf bank_mask:0xf bound_ctrl:1
	v_pk_fma_f32 v[110:111], v[60:61], v[52:53], v[110:111] op_sel_hi:[1,0,1]
	v_pk_fma_f32 v[112:113], v[60:61], v[52:53], v[112:113] op_sel:[0,1,0]
	v_pk_fma_f32 v[144:145], v[60:61], v[54:55], v[144:145] op_sel_hi:[1,0,1]
	v_pk_fma_f32 v[146:147], v[60:61], v[54:55], v[146:147] op_sel:[0,1,0]
	v_pk_fma_f32 v[64:65], v[106:107], v[48:49], v[110:111] op_sel_hi:[1,0,1]
	v_pk_fma_f32 v[66:67], v[106:107], v[48:49], v[112:113] op_sel:[0,1,0]
	v_pk_fma_f32 v[68:69], v[106:107], v[50:51], v[144:145] op_sel_hi:[1,0,1]
	v_pk_fma_f32 v[70:71], v[106:107], v[50:51], v[146:147] op_sel:[0,1,0]
	s_waitcnt lgkmcnt(0)
	v_pk_mul_f32 v[106:107], v[64:65], v[76:77] op_sel_hi:[1,0]
	ds_read_b128 v[40:43], v175 offset:17920
	v_pk_mul_f32 v[108:109], v[64:65], v[88:89] op_sel_hi:[1,0]
	ds_read_b128 v[44:47], v175 offset:17936
	v_pk_fma_f32 v[106:107], v[66:67], v[76:77], v[106:107] op_sel:[0,1,0]
	ds_read_b128 v[48:51], v175 offset:17952
	v_pk_fma_f32 v[108:109], v[66:67], v[88:89], v[108:109] op_sel:[0,1,0]
	ds_read_b128 v[52:55], v175 offset:17968
	v_pk_fma_f32 v[106:107], v[68:69], v[78:79], v[106:107] op_sel_hi:[1,0,1]
	ds_read_b128 v[56:59], v175 offset:17984
	v_pk_fma_f32 v[108:109], v[68:69], v[90:91], v[108:109] op_sel_hi:[1,0,1]
	ds_read_b128 v[60:63], v123 offset:44544
	v_pk_fma_f32 v[106:107], v[70:71], v[78:79], v[106:107] op_sel:[0,1,0]
	v_pk_fma_f32 v[108:109], v[70:71], v[90:91], v[108:109] op_sel:[0,1,0]
	v_pk_mul_f32 v[110:111], v[64:65], v[72:73] op_sel_hi:[1,0]
	v_add_f32_dpp v106, v106, v106 quad_perm:[1,0,3,2] row_mask:0xf bank_mask:0xf bound_ctrl:1
	v_add_f32_dpp v107, v107, v107 quad_perm:[1,0,3,2] row_mask:0xf bank_mask:0xf bound_ctrl:1
	v_pk_fma_f32 v[108:109], v[94:95], v[176:177], v[108:109]
	v_pk_mul_f32 v[112:113], v[66:67], v[72:73] op_sel:[0,1]
	v_add_f32_dpp v106, v106, v106 quad_perm:[2,3,0,1] row_mask:0xf bank_mask:0xf bound_ctrl:1
	v_add_f32_dpp v107, v107, v107 quad_perm:[2,3,0,1] row_mask:0xf bank_mask:0xf bound_ctrl:1
	v_add_f32_dpp v149, v108, v108 row_half_mirror row_mask:0xf bank_mask:0xf bound_ctrl:1
	v_add_f32_dpp v149, v109, v109 row_half_mirror row_mask:0xf bank_mask:0xa
	v_add_f32_dpp v106, v106, v106 row_half_mirror row_mask:0xf bank_mask:0xf bound_ctrl:1
	v_add_f32_dpp v107, v107, v107 row_half_mirror row_mask:0xf bank_mask:0xf bound_ctrl:1
	v_pk_mul_f32 v[144:145], v[68:69], v[74:75] op_sel_hi:[1,0]
	v_pk_mul_f32 v[146:147], v[70:71], v[74:75] op_sel:[0,1]
	v_add_f32_dpp v150, v148, v148 row_ror:8 row_mask:0xf bank_mask:0xf bound_ctrl:1
	v_add_f32_dpp v150, v149, v149 row_ror:8 row_mask:0xf bank_mask:0xc
	v_add_f32_dpp v106, v106, v106 row_mirror row_mask:0xf bank_mask:0xf bound_ctrl:1
	v_add_f32_dpp v107, v107, v107 row_mirror row_mask:0xf bank_mask:0xf bound_ctrl:1
	v_pk_fma_f32 v[110:111], v[92:93], v[84:85], v[110:111] op_sel_hi:[1,0,1]
	v_pk_fma_f32 v[112:113], v[92:93], v[84:85], v[112:113] op_sel:[0,1,0]
	v_pk_fma_f32 v[144:145], v[92:93], v[86:87], v[144:145] op_sel_hi:[1,0,1]
	v_pk_fma_f32 v[146:147], v[92:93], v[86:87], v[146:147] op_sel:[0,1,0]
	v_add_f32_dpp v150, v150, v150 quad_perm:[1,0,3,2] row_mask:0xf bank_mask:0xf bound_ctrl:1
	v_pk_fma_f32 v[64:65], v[106:107], v[80:81], v[110:111] op_sel_hi:[1,0,1]
	v_pk_fma_f32 v[66:67], v[106:107], v[80:81], v[112:113] op_sel:[0,1,0]
	v_add_f32_dpp v150, v150, v150 quad_perm:[2,3,0,1] row_mask:0xf bank_mask:0xf bound_ctrl:1
	v_pk_fma_f32 v[68:69], v[106:107], v[82:83], v[144:145] op_sel_hi:[1,0,1]
	v_pk_fma_f32 v[70:71], v[106:107], v[82:83], v[146:147] op_sel:[0,1,0]
	s_mov_b64 exec, s[34:35]
	ds_write_b32 v178, v150 offset:1536
	s_mov_b64 exec, -1
	s_waitcnt lgkmcnt(1)
; #define SC_GET(X, t) do { const float* p = rec + (t) * 320; w##X = *(const f32x4*)p; a##X = *(const f32x4*)(p + 4); b##X = *(const f32x4*)(p + 8); k##X = *(const f32x4*)(p + 12); q##X = *(const f32x4*)(p + 16); \
;                 v##X = *(const f32x4*)(VVa + (t) * 64); } while (0)
; DI void scan_phase(unsigned char* lds, const Ctx& a, const Op& d, const int variant) {
;     ...
;                 SC_GET(A, 0);
; #pragma unroll 2
;                 for (int t = 0; t < SC_T; t += 2) {
;                     SC_GET(B, t + 1);
;                     SC_STEP(A, t);
;                     if (t + 2 < SC_T) SC_GET(A, t + 2);
;                     SC_STEP(B, t + 1);
;                 }
	v_pk_mul_f32 v[106:107], v[64:65], v[44:45] op_sel_hi:[1,0]
	ds_read_b128 v[72:75], v175 offset:19200
	v_pk_mul_f32 v[108:109], v[64:65], v[56:57] op_sel_hi:[1,0]
	ds_read_b128 v[76:79], v175 offset:19216
	v_pk_fma_f32 v[106:107], v[66:67], v[44:45], v[106:107] op_sel:[0,1,0]
	ds_read_b128 v[80:83], v175 offset:19232
	v_pk_fma_f32 v[108:109], v[66:67], v[56:57], v[108:109] op_sel:[0,1,0]
	ds_read_b128 v[84:87], v175 offset:19248
	v_pk_fma_f32 v[106:107], v[68:69], v[46:47], v[106:107] op_sel_hi:[1,0,1]
	ds_read_b128 v[88:91], v175 offset:19264
	v_pk_fma_f32 v[108:109], v[68:69], v[58:59], v[108:109] op_sel_hi:[1,0,1]
	ds_read_b128 v[92:95], v123 offset:44800
	v_pk_fma_f32 v[106:107], v[70:71], v[46:47], v[106:107] op_sel:[0,1,0]
	v_pk_fma_f32 v[108:109], v[70:71], v[58:59], v[108:109] op_sel:[0,1,0]
	v_pk_mul_f32 v[110:111], v[64:65], v[40:41] op_sel_hi:[1,0]
	v_add_f32_dpp v106, v106, v106 quad_perm:[1,0,3,2] row_mask:0xf bank_mask:0xf bound_ctrl:1
	v_add_f32_dpp v107, v107, v107 quad_perm:[1,0,3,2] row_mask:0xf bank_mask:0xf bound_ctrl:1
	v_pk_fma_f32 v[108:109], v[62:63], v[176:177], v[108:109]
	v_pk_mul_f32 v[112:113], v[66:67], v[40:41] op_sel:[0,1]
	v_add_f32_dpp v106, v106, v106 quad_perm:[2,3,0,1] row_mask:0xf bank_mask:0xf bound_ctrl:1
	v_add_f32_dpp v107, v107, v107 quad_perm:[2,3,0,1] row_mask:0xf bank_mask:0xf bound_ctrl:1
	v_add_f32_dpp v148, v108, v108 row_half_mirror row_mask:0xf bank_mask:0xf bound_ctrl:1
	v_add_f32_dpp v148, v109, v109 row_half_mirror row_mask:0xf bank_mask:0xa
	v_add_f32_dpp v106, v106, v106 row_half_mirror row_mask:0xf bank_mask:0xf bound_ctrl:1
	v_add_f32_dpp v107, v107, v107 row_half_mirror row_mask:0xf bank_mask:0xf bound_ctrl:1
	v_pk_mul_f32 v[144:145], v[68:69], v[42:43] op_sel_hi:[1,0]
	v_pk_mul_f32 v[146:147], v[70:71], v[42:43] op_sel:[0,1]
	v_add_f32_dpp v106, v106, v106 row_mirror row_mask:0xf bank_mask:0xf bound_ctrl:1
	v_add_f32_dpp v107, v107, v107 row_mirror row_mask:0xf bank_mask:0xf bound_ctrl:1
	v_pk_fma_f32 v[110:111], v[60:61], v[52:53], v[110:111] op_sel_hi:[1,0,1]
	v_pk_fma_f32 v[112:113], v[60:61], v[52:53], v[112:113] op_sel:[0,1,0]
	v_pk_fma_f32 v[144:145], v[60:61], v[54:55], v[144:145] op_sel_hi:[1,0,1]
	v_pk_fma_f32 v[146:147], v[60:61], v[54:55], v[146:147] op_sel:[0,1,0]
	v_pk_fma_f32 v[64:65], v[106:107], v[48:49], v[110:111] op_sel_hi:[1,0,1]
	v_pk_fma_f32 v[66:67], v[106:107], v[48:49], v[112:113] op_sel:[0,1,0]
	v_pk_fma_f32 v[68:69], v[106:107], v[50:51], v[144:145] op_sel_hi:[1,0,1]
	v_pk_fma_f32 v[70:71], v[106:107], v[50:51], v[146:147] op_sel:[0,1,0]
	s_waitcnt lgkmcnt(0)
	v_pk_mul_f32 v[106:107], v[64:65], v[76:77] op_sel_hi:[1,0]
	ds_read_b128 v[40:43], v175 offset:20480
	v_pk_mul_f32 v[108:109], v[64:65], v[88:89] op_sel_hi:[1,0]
	ds_read_b128 v[44:47], v175 offset:20496
	v_pk_fma_f32 v[106:107], v[66:67], v[76:77], v[106:107] op_sel:[0,1,0]
	ds_read_b128 v[48:51], v175 offset:20512
	v_pk_fma_f32 v[108:109], v[66:67], v[88:89], v[108:109] op_sel:[0,1,0]
	ds_read_b128 v[52:55], v175 offset:20528
	v_pk_fma_f32 v[106:107], v[68:69], v[78:79], v[106:107] op_sel_hi:[1,0,1]
	ds_read_b128 v[56:59], v175 offset:20544
	v_pk_fma_f32 v[108:109], v[68:69], v[90:91], v[108:109] op_sel_hi:[1,0,1]
	ds_read_b128 v[60:63], v123 offset:45056
	v_pk_fma_f32 v[106:107], v[70:71], v[78:79], v[106:107] op_sel:[0,1,0]
	v_pk_fma_f32 v[108:109], v[70:71], v[90:91], v[108:109] op_sel:[0,1,0]
	v_pk_mul_f32 v[110:111], v[64:65], v[72:73] op_sel_hi:[1,0]
	v_add_f32_dpp v106, v106, v106 quad_perm:[1,0,3,2] row_mask:0xf bank_mask:0xf bound_ctrl:1
	v_add_f32_dpp v107, v107, v107 quad_perm:[1,0,3,2] row_mask:0xf bank_mask:0xf bound_ctrl:1
	v_pk_fma_f32 v[108:109], v[94:95], v[176:177], v[108:109]
	v_pk_mul_f32 v[112:113], v[66:67], v[72:73] op_sel:[0,1]
	v_add_f32_dpp v106, v106, v106 quad_perm:[2,3,0,1] row_mask:0xf bank_mask:0xf bound_ctrl:1
	v_add_f32_dpp v107, v107, v107 quad_perm:[2,3,0,1] row_mask:0xf bank_mask:0xf bound_ctrl:1
	v_add_f32_dpp v149, v108, v108 row_half_mirror row_mask:0xf bank_mask:0xf bound_ctrl:1
	v_add_f32_dpp v149, v109, v109 row_half_mirror row_mask:0xf bank_mask:0xa
	v_add_f32_dpp v106, v106, v106 row_half_mirror row_mask:0xf bank_mask:0xf bound_ctrl:1
	v_add_f32_dpp v107, v107, v107 row_half_mirror row_mask:0xf bank_mask:0xf bound_ctrl:1
	v_pk_mul_f32 v[144:145], v[68:69], v[74:75] op_sel_hi:[1,0]
	v_pk_mul_f32 v[146:147], v[70:71], v[74:75] op_sel:[0,1]
	v_add_f32_dpp v150, v148, v148 row_ror:8 row_mask:0xf bank_mask:0xf bound_ctrl:1
	v_add_f32_dpp v150, v149, v149 row_ror:8 row_mask:0xf bank_mask:0xc
	v_add_f32_dpp v106, v106, v106 row_mirror row_mask:0xf bank_mask:0xf bound_ctrl:1
	v_add_f32_dpp v107, v107, v107 row_mirror row_mask:0xf bank_mask:0xf bound_ctrl:1
	v_pk_fma_f32 v[110:111], v[92:93], v[84:85], v[110:111] op_sel_hi:[1,0,1]
	v_pk_fma_f32 v[112:113], v[92:93], v[84:85], v[112:113] op_sel:[0,1,0]
	v_pk_fma_f32 v[144:145], v[92:93], v[86:87], v[144:145] op_sel_hi:[1,0,1]
	v_pk_fma_f32 v[146:147], v[92:93], v[86:87], v[146:147] op_sel:[0,1,0]
	v_add_f32_dpp v150, v150, v150 quad_perm:[1,0,3,2] row_mask:0xf bank_mask:0xf bound_ctrl:1
	v_pk_fma_f32 v[64:65], v[106:107], v[80:81], v[110:111] op_sel_hi:[1,0,1]
	v_pk_fma_f32 v[66:67], v[106:107], v[80:81], v[112:113] op_sel:[0,1,0]
	v_add_f32_dpp v150, v150, v150 quad_perm:[2,3,0,1] row_mask:0xf bank_mask:0xf bound_ctrl:1
	v_pk_fma_f32 v[68:69], v[106:107], v[82:83], v[144:145] op_sel_hi:[1,0,1]
	v_pk_fma_f32 v[70:71], v[106:107], v[82:83], v[146:147] op_sel:[0,1,0]
	s_mov_b64 exec, s[34:35]
	ds_write_b32 v178, v150 offset:1792
	s_mov_b64 exec, -1
	s_waitcnt lgkmcnt(1)
; #define SC_GET(X, t) do { const float* p = rec + (t) * 320; w##X = *(const f32x4*)p; a##X = *(const f32x4*)(p + 4); b##X = *(const f32x4*)(p + 8); k##X = *(const f32x4*)(p + 12); q##X = *(const f32x4*)(p + 16); \
;                 v##X = *(const f32x4*)(VVa + (t) * 64); } while (0)
; DI void scan_phase(unsigned char* lds, const Ctx& a, const Op& d, const int variant) {
;     ...
;                 SC_GET(A, 0);
; #pragma unroll 2
;                 for (int t = 0; t < SC_T; t += 2) {
;                     SC_GET(B, t + 1);
;                     SC_STEP(A, t);
;                     if (t + 2 < SC_T) SC_GET(A, t + 2);
;                     SC_STEP(B, t + 1);
;                 }
	v_pk_mul_f32 v[106:107], v[64:65], v[44:45] op_sel_hi:[1,0]
	ds_read_b128 v[72:75], v175 offset:21760
	v_pk_mul_f32 v[108:109], v[64:65], v[56:57] op_sel_hi:[1,0]
	ds_read_b128 v[76:79], v175 offset:21776
	v_pk_fma_f32 v[106:107], v[66:67], v[44:45], v[106:107] op_sel:[0,1,0]
	ds_read_b128 v[80:83], v175 offset:21792
	v_pk_fma_f32 v[108:109], v[66:67], v[56:57], v[108:109] op_sel:[0,1,0]
	ds_read_b128 v[84:87], v175 offset:21808
	v_pk_fma_f32 v[106:107], v[68:69], v[46:47], v[106:107] op_sel_hi:[1,0,1]
	ds_read_b128 v[88:91], v175 offset:21824
	v_pk_fma_f32 v[108:109], v[68:69], v[58:59], v[108:109] op_sel_hi:[1,0,1]
	ds_read_b128 v[92:95], v123 offset:45312
	v_pk_fma_f32 v[106:107], v[70:71], v[46:47], v[106:107] op_sel:[0,1,0]
	v_pk_fma_f32 v[108:109], v[70:71], v[58:59], v[108:109] op_sel:[0,1,0]
	v_pk_mul_f32 v[110:111], v[64:65], v[40:41] op_sel_hi:[1,0]
	v_add_f32_dpp v106, v106, v106 quad_perm:[1,0,3,2] row_mask:0xf bank_mask:0xf bound_ctrl:1
	v_add_f32_dpp v107, v107, v107 quad_perm:[1,0,3,2] row_mask:0xf bank_mask:0xf bound_ctrl:1
	v_pk_fma_f32 v[108:109], v[62:63], v[176:177], v[108:109]
	v_pk_mul_f32 v[112:113], v[66:67], v[40:41] op_sel:[0,1]
	v_add_f32_dpp v106, v106, v106 quad_perm:[2,3,0,1] row_mask:0xf bank_mask:0xf bound_ctrl:1
	v_add_f32_dpp v107, v107, v107 quad_perm:[2,3,0,1] row_mask:0xf bank_mask:0xf bound_ctrl:1
	v_add_f32_dpp v148, v108, v108 row_half_mirror row_mask:0xf bank_mask:0xf bound_ctrl:1
	v_add_f32_dpp v148, v109, v109 row_half_mirror row_mask:0xf bank_mask:0xa
	v_add_f32_dpp v106, v106, v106 row_half_mirror row_mask:0xf bank_mask:0xf bound_ctrl:1
	v_add_f32_dpp v107, v107, v107 row_half_mirror row_mask:0xf bank_mask:0xf bound_ctrl:1
	v_pk_mul_f32 v[144:145], v[68:69], v[42:43] op_sel_hi:[1,0]
	v_pk_mul_f32 v[146:147], v[70:71], v[42:43] op_sel:[0,1]
	v_add_f32_dpp v106, v106, v106 row_mirror row_mask:0xf bank_mask:0xf bound_ctrl:1
	v_add_f32_dpp v107, v107, v107 row_mirror row_mask:0xf bank_mask:0xf bound_ctrl:1
	v_pk_fma_f32 v[110:111], v[60:61], v[52:53], v[110:111] op_sel_hi:[1,0,1]
	v_pk_fma_f32 v[112:113], v[60:61], v[52:53], v[112:113] op_sel:[0,1,0]
	v_pk_fma_f32 v[144:145], v[60:61], v[54:55], v[144:145] op_sel_hi:[1,0,1]
	v_pk_fma_f32 v[146:147], v[60:61], v[54:55], v[146:147] op_sel:[0,1,0]
	v_pk_fma_f32 v[64:65], v[106:107], v[48:49], v[110:111] op_sel_hi:[1,0,1]
	v_pk_fma_f32 v[66:67], v[106:107], v[48:49], v[112:113] op_sel:[0,1,0]
	v_pk_fma_f32 v[68:69], v[106:107], v[50:51], v[144:145] op_sel_hi:[1,0,1]
	v_pk_fma_f32 v[70:71], v[106:107], v[50:51], v[146:147] op_sel:[0,1,0]
	s_waitcnt lgkmcnt(0)
	v_pk_mul_f32 v[106:107], v[64:65], v[76:77] op_sel_hi:[1,0]
	ds_read_b128 v[40:43], v175 offset:23040
	v_pk_mul_f32 v[108:109], v[64:65], v[88:89] op_sel_hi:[1,0]
	ds_read_b128 v[44:47], v175 offset:23056
	v_pk_fma_f32 v[106:107], v[66:67], v[76:77], v[106:107] op_sel:[0,1,0]
	ds_read_b128 v[48:51], v175 offset:23072
	v_pk_fma_f32 v[108:109], v[66:67], v[88:89], v[108:109] op_sel:[0,1,0]
	ds_read_b128 v[52:55], v175 offset:23088
	v_pk_fma_f32 v[106:107], v[68:69], v[78:79], v[106:107] op_sel_hi:[1,0,1]
	ds_read_b128 v[56:59], v175 offset:23104
	v_pk_fma_f32 v[108:109], v[68:69], v[90:91], v[108:109] op_sel_hi:[1,0,1]
	ds_read_b128 v[60:63], v123 offset:45568
	v_pk_fma_f32 v[106:107], v[70:71], v[78:79], v[106:107] op_sel:[0,1,0]
	v_pk_fma_f32 v[108:109], v[70:71], v[90:91], v[108:109] op_sel:[0,1,0]
	v_pk_mul_f32 v[110:111], v[64:65], v[72:73] op_sel_hi:[1,0]
	v_add_f32_dpp v106, v106, v106 quad_perm:[1,0,3,2] row_mask:0xf bank_mask:0xf bound_ctrl:1
	v_add_f32_dpp v107, v107, v107 quad_perm:[1,0,3,2] row_mask:0xf bank_mask:0xf bound_ctrl:1
	v_pk_fma_f32 v[108:109], v[94:95], v[176:177], v[108:109]
	v_pk_mul_f32 v[112:113], v[66:67], v[72:73] op_sel:[0,1]
	v_add_f32_dpp v106, v106, v106 quad_perm:[2,3,0,1] row_mask:0xf bank_mask:0xf bound_ctrl:1
	v_add_f32_dpp v107, v107, v107 quad_perm:[2,3,0,1] row_mask:0xf bank_mask:0xf bound_ctrl:1
	v_add_f32_dpp v149, v108, v108 row_half_mirror row_mask:0xf bank_mask:0xf bound_ctrl:1
	v_add_f32_dpp v149, v109, v109 row_half_mirror row_mask:0xf bank_mask:0xa
	v_add_f32_dpp v106, v106, v106 row_half_mirror row_mask:0xf bank_mask:0xf bound_ctrl:1
	v_add_f32_dpp v107, v107, v107 row_half_mirror row_mask:0xf bank_mask:0xf bound_ctrl:1
	v_pk_mul_f32 v[144:145], v[68:69], v[74:75] op_sel_hi:[1,0]
	v_pk_mul_f32 v[146:147], v[70:71], v[74:75] op_sel:[0,1]
	v_add_f32_dpp v150, v148, v148 row_ror:8 row_mask:0xf bank_mask:0xf bound_ctrl:1
	v_add_f32_dpp v150, v149, v149 row_ror:8 row_mask:0xf bank_mask:0xc
	v_add_f32_dpp v106, v106, v106 row_mirror row_mask:0xf bank_mask:0xf bound_ctrl:1
	v_add_f32_dpp v107, v107, v107 row_mirror row_mask:0xf bank_mask:0xf bound_ctrl:1
	v_pk_fma_f32 v[110:111], v[92:93], v[84:85], v[110:111] op_sel_hi:[1,0,1]
	v_pk_fma_f32 v[112:113], v[92:93], v[84:85], v[112:113] op_sel:[0,1,0]
	v_pk_fma_f32 v[144:145], v[92:93], v[86:87], v[144:145] op_sel_hi:[1,0,1]
	v_pk_fma_f32 v[146:147], v[92:93], v[86:87], v[146:147] op_sel:[0,1,0]
	v_add_f32_dpp v150, v150, v150 quad_perm:[1,0,3,2] row_mask:0xf bank_mask:0xf bound_ctrl:1
	v_pk_fma_f32 v[64:65], v[106:107], v[80:81], v[110:111] op_sel_hi:[1,0,1]
	v_pk_fma_f32 v[66:67], v[106:107], v[80:81], v[112:113] op_sel:[0,1,0]
	v_add_f32_dpp v150, v150, v150 quad_perm:[2,3,0,1] row_mask:0xf bank_mask:0xf bound_ctrl:1
	v_pk_fma_f32 v[68:69], v[106:107], v[82:83], v[144:145] op_sel_hi:[1,0,1]
	v_pk_fma_f32 v[70:71], v[106:107], v[82:83], v[146:147] op_sel:[0,1,0]
	s_mov_b64 exec, s[34:35]
	ds_write_b32 v178, v150 offset:2048
	s_mov_b64 exec, -1
	s_waitcnt lgkmcnt(1)
; #define SC_GET(X, t) do { const float* p = rec + (t) * 320; w##X = *(const f32x4*)p; a##X = *(const f32x4*)(p + 4); b##X = *(const f32x4*)(p + 8); k##X = *(const f32x4*)(p + 12); q##X = *(const f32x4*)(p + 16); \
;                 v##X = *(const f32x4*)(VVa + (t) * 64); } while (0)
; DI void scan_phase(unsigned char* lds, const Ctx& a, const Op& d, const int variant) {
;     ...
;                 SC_GET(A, 0);
; #pragma unroll 2
;                 for (int t = 0; t < SC_T; t += 2) {
;                     SC_GET(B, t + 1);
;                     SC_STEP(A, t);
;                     if (t + 2 < SC_T) SC_GET(A, t + 2);
;                     SC_STEP(B, t + 1);
;                 }
	v_pk_mul_f32 v[106:107], v[64:65], v[44:45] op_sel_hi:[1,0]
	ds_read_b128 v[72:75], v175 offset:24320
	v_pk_mul_f32 v[108:109], v[64:65], v[56:57] op_sel_hi:[1,0]
	ds_read_b128 v[76:79], v175 offset:24336
	v_pk_fma_f32 v[106:107], v[66:67], v[44:45], v[106:107] op_sel:[0,1,0]
	ds_read_b128 v[80:83], v175 offset:24352
	v_pk_fma_f32 v[108:109], v[66:67], v[56:57], v[108:109] op_sel:[0,1,0]
	ds_read_b128 v[84:87], v175 offset:24368
	v_pk_fma_f32 v[106:107], v[68:69], v[46:47], v[106:107] op_sel_hi:[1,0,1]
	ds_read_b128 v[88:91], v175 offset:24384
	v_pk_fma_f32 v[108:109], v[68:69], v[58:59], v[108:109] op_sel_hi:[1,0,1]
	ds_read_b128 v[92:95], v123 offset:45824
	v_pk_fma_f32 v[106:107], v[70:71], v[46:47], v[106:107] op_sel:[0,1,0]
	v_pk_fma_f32 v[108:109], v[70:71], v[58:59], v[108:109] op_sel:[0,1,0]
	v_pk_mul_f32 v[110:111], v[64:65], v[40:41] op_sel_hi:[1,0]
	v_add_f32_dpp v106, v106, v106 quad_perm:[1,0,3,2] row_mask:0xf bank_mask:0xf bound_ctrl:1
	v_add_f32_dpp v107, v107, v107 quad_perm:[1,0,3,2] row_mask:0xf bank_mask:0xf bound_ctrl:1
	v_pk_fma_f32 v[108:109], v[62:63], v[176:177], v[108:109]
	v_pk_mul_f32 v[112:113], v[66:67], v[40:41] op_sel:[0,1]
	v_add_f32_dpp v106, v106, v106 quad_perm:[2,3,0,1] row_mask:0xf bank_mask:0xf bound_ctrl:1
	v_add_f32_dpp v107, v107, v107 quad_perm:[2,3,0,1] row_mask:0xf bank_mask:0xf bound_ctrl:1
	v_add_f32_dpp v148, v108, v108 row_half_mirror row_mask:0xf bank_mask:0xf bound_ctrl:1
	v_add_f32_dpp v148, v109, v109 row_half_mirror row_mask:0xf bank_mask:0xa
	v_add_f32_dpp v106, v106, v106 row_half_mirror row_mask:0xf bank_mask:0xf bound_ctrl:1
	v_add_f32_dpp v107, v107, v107 row_half_mirror row_mask:0xf bank_mask:0xf bound_ctrl:1
	v_pk_mul_f32 v[144:145], v[68:69], v[42:43] op_sel_hi:[1,0]
	v_pk_mul_f32 v[146:147], v[70:71], v[42:43] op_sel:[0,1]
	v_add_f32_dpp v106, v106, v106 row_mirror row_mask:0xf bank_mask:0xf bound_ctrl:1
	v_add_f32_dpp v107, v107, v107 row_mirror row_mask:0xf bank_mask:0xf bound_ctrl:1
	v_pk_fma_f32 v[110:111], v[60:61], v[52:53], v[110:111] op_sel_hi:[1,0,1]
	v_pk_fma_f32 v[112:113], v[60:61], v[52:53], v[112:113] op_sel:[0,1,0]
	v_pk_fma_f32 v[144:145], v[60:61], v[54:55], v[144:145] op_sel_hi:[1,0,1]
	v_pk_fma_f32 v[146:147], v[60:61], v[54:55], v[146:147] op_sel:[0,1,0]
	v_pk_fma_f32 v[64:65], v[106:107], v[48:49], v[110:111] op_sel_hi:[1,0,1]
	v_pk_fma_f32 v[66:67], v[106:107], v[48:49], v[112:113] op_sel:[0,1,0]
	v_pk_fma_f32 v[68:69], v[106:107], v[50:51], v[144:145] op_sel_hi:[1,0,1]
	v_pk_fma_f32 v[70:71], v[106:107], v[50:51], v[146:147] op_sel:[0,1,0]
	s_waitcnt lgkmcnt(0)
	v_pk_mul_f32 v[106:107], v[64:65], v[76:77] op_sel_hi:[1,0]
	ds_read_b128 v[40:43], v175 offset:25600
	v_pk_mul_f32 v[108:109], v[64:65], v[88:89] op_sel_hi:[1,0]
	ds_read_b128 v[44:47], v175 offset:25616
	v_pk_fma_f32 v[106:107], v[66:67], v[76:77], v[106:107] op_sel:[0,1,0]
	ds_read_b128 v[48:51], v175 offset:25632
	v_pk_fma_f32 v[108:109], v[66:67], v[88:89], v[108:109] op_sel:[0,1,0]
	ds_read_b128 v[52:55], v175 offset:25648
	v_pk_fma_f32 v[106:107], v[68:69], v[78:79], v[106:107] op_sel_hi:[1,0,1]
	ds_read_b128 v[56:59], v175 offset:25664
	v_pk_fma_f32 v[108:109], v[68:69], v[90:91], v[108:109] op_sel_hi:[1,0,1]
	ds_read_b128 v[60:63], v123 offset:46080
	v_pk_fma_f32 v[106:107], v[70:71], v[78:79], v[106:107] op_sel:[0,1,0]
	v_pk_fma_f32 v[108:109], v[70:71], v[90:91], v[108:109] op_sel:[0,1,0]
	v_pk_mul_f32 v[110:111], v[64:65], v[72:73] op_sel_hi:[1,0]
	v_add_f32_dpp v106, v106, v106 quad_perm:[1,0,3,2] row_mask:0xf bank_mask:0xf bound_ctrl:1
	v_add_f32_dpp v107, v107, v107 quad_perm:[1,0,3,2] row_mask:0xf bank_mask:0xf bound_ctrl:1
	v_pk_fma_f32 v[108:109], v[94:95], v[176:177], v[108:109]
	v_pk_mul_f32 v[112:113], v[66:67], v[72:73] op_sel:[0,1]
	v_add_f32_dpp v106, v106, v106 quad_perm:[2,3,0,1] row_mask:0xf bank_mask:0xf bound_ctrl:1
	v_add_f32_dpp v107, v107, v107 quad_perm:[2,3,0,1] row_mask:0xf bank_mask:0xf bound_ctrl:1
	v_add_f32_dpp v149, v108, v108 row_half_mirror row_mask:0xf bank_mask:0xf bound_ctrl:1
	v_add_f32_dpp v149, v109, v109 row_half_mirror row_mask:0xf bank_mask:0xa
	v_add_f32_dpp v106, v106, v106 row_half_mirror row_mask:0xf bank_mask:0xf bound_ctrl:1
	v_add_f32_dpp v107, v107, v107 row_half_mirror row_mask:0xf bank_mask:0xf bound_ctrl:1
	v_pk_mul_f32 v[144:145], v[68:69], v[74:75] op_sel_hi:[1,0]
	v_pk_mul_f32 v[146:147], v[70:71], v[74:75] op_sel:[0,1]
	v_add_f32_dpp v150, v148, v148 row_ror:8 row_mask:0xf bank_mask:0xf bound_ctrl:1
	v_add_f32_dpp v150, v149, v149 row_ror:8 row_mask:0xf bank_mask:0xc
	v_add_f32_dpp v106, v106, v106 row_mirror row_mask:0xf bank_mask:0xf bound_ctrl:1
	v_add_f32_dpp v107, v107, v107 row_mirror row_mask:0xf bank_mask:0xf bound_ctrl:1
	v_pk_fma_f32 v[110:111], v[92:93], v[84:85], v[110:111] op_sel_hi:[1,0,1]
	v_pk_fma_f32 v[112:113], v[92:93], v[84:85], v[112:113] op_sel:[0,1,0]
	v_pk_fma_f32 v[144:145], v[92:93], v[86:87], v[144:145] op_sel_hi:[1,0,1]
	v_pk_fma_f32 v[146:147], v[92:93], v[86:87], v[146:147] op_sel:[0,1,0]
	v_add_f32_dpp v150, v150, v150 quad_perm:[1,0,3,2] row_mask:0xf bank_mask:0xf bound_ctrl:1
	v_pk_fma_f32 v[64:65], v[106:107], v[80:81], v[110:111] op_sel_hi:[1,0,1]
	v_pk_fma_f32 v[66:67], v[106:107], v[80:81], v[112:113] op_sel:[0,1,0]
	v_add_f32_dpp v150, v150, v150 quad_perm:[2,3,0,1] row_mask:0xf bank_mask:0xf bound_ctrl:1
	v_pk_fma_f32 v[68:69], v[106:107], v[82:83], v[144:145] op_sel_hi:[1,0,1]
	v_pk_fma_f32 v[70:71], v[106:107], v[82:83], v[146:147] op_sel:[0,1,0]
	s_mov_b64 exec, s[34:35]
	ds_write_b32 v178, v150 offset:2304
	s_mov_b64 exec, -1
	s_waitcnt lgkmcnt(1)
; #define SC_GET(X, t) do { const float* p = rec + (t) * 320; w##X = *(const f32x4*)p; a##X = *(const f32x4*)(p + 4); b##X = *(const f32x4*)(p + 8); k##X = *(const f32x4*)(p + 12); q##X = *(const f32x4*)(p + 16); \
;                 v##X = *(const f32x4*)(VVa + (t) * 64); } while (0)
; DI void scan_phase(unsigned char* lds, const Ctx& a, const Op& d, const int variant) {
;     ...
;                 SC_GET(A, 0);
; #pragma unroll 2
;                 for (int t = 0; t < SC_T; t += 2) {
;                     SC_GET(B, t + 1);
;                     SC_STEP(A, t);
;                     if (t + 2 < SC_T) SC_GET(A, t + 2);
;                     SC_STEP(B, t + 1);
;                 }
	v_pk_mul_f32 v[106:107], v[64:65], v[44:45] op_sel_hi:[1,0]
	ds_read_b128 v[72:75], v175 offset:26880
	v_pk_mul_f32 v[108:109], v[64:65], v[56:57] op_sel_hi:[1,0]
	ds_read_b128 v[76:79], v175 offset:26896
	v_pk_fma_f32 v[106:107], v[66:67], v[44:45], v[106:107] op_sel:[0,1,0]
	ds_read_b128 v[80:83], v175 offset:26912
	v_pk_fma_f32 v[108:109], v[66:67], v[56:57], v[108:109] op_sel:[0,1,0]
	ds_read_b128 v[84:87], v175 offset:26928
	v_pk_fma_f32 v[106:107], v[68:69], v[46:47], v[106:107] op_sel_hi:[1,0,1]
	ds_read_b128 v[88:91], v175 offset:26944
	v_pk_fma_f32 v[108:109], v[68:69], v[58:59], v[108:109] op_sel_hi:[1,0,1]
	ds_read_b128 v[92:95], v123 offset:46336
	v_pk_fma_f32 v[106:107], v[70:71], v[46:47], v[106:107] op_sel:[0,1,0]
	v_pk_fma_f32 v[108:109], v[70:71], v[58:59], v[108:109] op_sel:[0,1,0]
	v_pk_mul_f32 v[110:111], v[64:65], v[40:41] op_sel_hi:[1,0]
	v_add_f32_dpp v106, v106, v106 quad_perm:[1,0,3,2] row_mask:0xf bank_mask:0xf bound_ctrl:1
	v_add_f32_dpp v107, v107, v107 quad_perm:[1,0,3,2] row_mask:0xf bank_mask:0xf bound_ctrl:1
	v_pk_fma_f32 v[108:109], v[62:63], v[176:177], v[108:109]
	v_pk_mul_f32 v[112:113], v[66:67], v[40:41] op_sel:[0,1]
	v_add_f32_dpp v106, v106, v106 quad_perm:[2,3,0,1] row_mask:0xf bank_mask:0xf bound_ctrl:1
	v_add_f32_dpp v107, v107, v107 quad_perm:[2,3,0,1] row_mask:0xf bank_mask:0xf bound_ctrl:1
	v_add_f32_dpp v148, v108, v108 row_half_mirror row_mask:0xf bank_mask:0xf bound_ctrl:1
	v_add_f32_dpp v148, v109, v109 row_half_mirror row_mask:0xf bank_mask:0xa
	v_add_f32_dpp v106, v106, v106 row_half_mirror row_mask:0xf bank_mask:0xf bound_ctrl:1
	v_add_f32_dpp v107, v107, v107 row_half_mirror row_mask:0xf bank_mask:0xf bound_ctrl:1
	v_pk_mul_f32 v[144:145], v[68:69], v[42:43] op_sel_hi:[1,0]
	v_pk_mul_f32 v[146:147], v[70:71], v[42:43] op_sel:[0,1]
	v_add_f32_dpp v106, v106, v106 row_mirror row_mask:0xf bank_mask:0xf bound_ctrl:1
	v_add_f32_dpp v107, v107, v107 row_mirror row_mask:0xf bank_mask:0xf bound_ctrl:1
	v_pk_fma_f32 v[110:111], v[60:61], v[52:53], v[110:111] op_sel_hi:[1,0,1]
	v_pk_fma_f32 v[112:113], v[60:61], v[52:53], v[112:113] op_sel:[0,1,0]
	v_pk_fma_f32 v[144:145], v[60:61], v[54:55], v[144:145] op_sel_hi:[1,0,1]
	v_pk_fma_f32 v[146:147], v[60:61], v[54:55], v[146:147] op_sel:[0,1,0]
	v_pk_fma_f32 v[64:65], v[106:107], v[48:49], v[110:111] op_sel_hi:[1,0,1]
	v_pk_fma_f32 v[66:67], v[106:107], v[48:49], v[112:113] op_sel:[0,1,0]
	v_pk_fma_f32 v[68:69], v[106:107], v[50:51], v[144:145] op_sel_hi:[1,0,1]
	v_pk_fma_f32 v[70:71], v[106:107], v[50:51], v[146:147] op_sel:[0,1,0]
	s_waitcnt lgkmcnt(0)
	v_pk_mul_f32 v[106:107], v[64:65], v[76:77] op_sel_hi:[1,0]
	ds_read_b128 v[40:43], v175 offset:28160
	v_pk_mul_f32 v[108:109], v[64:65], v[88:89] op_sel_hi:[1,0]
	ds_read_b128 v[44:47], v175 offset:28176
	v_pk_fma_f32 v[106:107], v[66:67], v[76:77], v[106:107] op_sel:[0,1,0]
	ds_read_b128 v[48:51], v175 offset:28192
	v_pk_fma_f32 v[108:109], v[66:67], v[88:89], v[108:109] op_sel:[0,1,0]
	ds_read_b128 v[52:55], v175 offset:28208
	v_pk_fma_f32 v[106:107], v[68:69], v[78:79], v[106:107] op_sel_hi:[1,0,1]
	ds_read_b128 v[56:59], v175 offset:28224
	v_pk_fma_f32 v[108:109], v[68:69], v[90:91], v[108:109] op_sel_hi:[1,0,1]
	ds_read_b128 v[60:63], v123 offset:46592
	v_pk_fma_f32 v[106:107], v[70:71], v[78:79], v[106:107] op_sel:[0,1,0]
	v_pk_fma_f32 v[108:109], v[70:71], v[90:91], v[108:109] op_sel:[0,1,0]
	v_pk_mul_f32 v[110:111], v[64:65], v[72:73] op_sel_hi:[1,0]
	v_add_f32_dpp v106, v106, v106 quad_perm:[1,0,3,2] row_mask:0xf bank_mask:0xf bound_ctrl:1
	v_add_f32_dpp v107, v107, v107 quad_perm:[1,0,3,2] row_mask:0xf bank_mask:0xf bound_ctrl:1
	v_pk_fma_f32 v[108:109], v[94:95], v[176:177], v[108:109]
	v_pk_mul_f32 v[112:113], v[66:67], v[72:73] op_sel:[0,1]
	v_add_f32_dpp v106, v106, v106 quad_perm:[2,3,0,1] row_mask:0xf bank_mask:0xf bound_ctrl:1
	v_add_f32_dpp v107, v107, v107 quad_perm:[2,3,0,1] row_mask:0xf bank_mask:0xf bound_ctrl:1
	v_add_f32_dpp v149, v108, v108 row_half_mirror row_mask:0xf bank_mask:0xf bound_ctrl:1
	v_add_f32_dpp v149, v109, v109 row_half_mirror row_mask:0xf bank_mask:0xa
	v_add_f32_dpp v106, v106, v106 row_half_mirror row_mask:0xf bank_mask:0xf bound_ctrl:1
	v_add_f32_dpp v107, v107, v107 row_half_mirror row_mask:0xf bank_mask:0xf bound_ctrl:1
	v_pk_mul_f32 v[144:145], v[68:69], v[74:75] op_sel_hi:[1,0]
	v_pk_mul_f32 v[146:147], v[70:71], v[74:75] op_sel:[0,1]
	v_add_f32_dpp v150, v148, v148 row_ror:8 row_mask:0xf bank_mask:0xf bound_ctrl:1
	v_add_f32_dpp v150, v149, v149 row_ror:8 row_mask:0xf bank_mask:0xc
	v_add_f32_dpp v106, v106, v106 row_mirror row_mask:0xf bank_mask:0xf bound_ctrl:1
	v_add_f32_dpp v107, v107, v107 row_mirror row_mask:0xf bank_mask:0xf bound_ctrl:1
	v_pk_fma_f32 v[110:111], v[92:93], v[84:85], v[110:111] op_sel_hi:[1,0,1]
	v_pk_fma_f32 v[112:113], v[92:93], v[84:85], v[112:113] op_sel:[0,1,0]
	v_pk_fma_f32 v[144:145], v[92:93], v[86:87], v[144:145] op_sel_hi:[1,0,1]
	v_pk_fma_f32 v[146:147], v[92:93], v[86:87], v[146:147] op_sel:[0,1,0]
	v_add_f32_dpp v150, v150, v150 quad_perm:[1,0,3,2] row_mask:0xf bank_mask:0xf bound_ctrl:1
	v_pk_fma_f32 v[64:65], v[106:107], v[80:81], v[110:111] op_sel_hi:[1,0,1]
	v_pk_fma_f32 v[66:67], v[106:107], v[80:81], v[112:113] op_sel:[0,1,0]
	v_add_f32_dpp v150, v150, v150 quad_perm:[2,3,0,1] row_mask:0xf bank_mask:0xf bound_ctrl:1
	v_pk_fma_f32 v[68:69], v[106:107], v[82:83], v[144:145] op_sel_hi:[1,0,1]
	v_pk_fma_f32 v[70:71], v[106:107], v[82:83], v[146:147] op_sel:[0,1,0]
	s_mov_b64 exec, s[34:35]
	ds_write_b32 v178, v150 offset:2560
	s_mov_b64 exec, -1
	s_waitcnt lgkmcnt(1)
; #define SC_GET(X, t) do { const float* p = rec + (t) * 320; w##X = *(const f32x4*)p; a##X = *(const f32x4*)(p + 4); b##X = *(const f32x4*)(p + 8); k##X = *(const f32x4*)(p + 12); q##X = *(const f32x4*)(p + 16); \
;                 v##X = *(const f32x4*)(VVa + (t) * 64); } while (0)
; DI void scan_phase(unsigned char* lds, const Ctx& a, const Op& d, const int variant) {
;     ...
;                 SC_GET(A, 0);
; #pragma unroll 2
;                 for (int t = 0; t < SC_T; t += 2) {
;                     SC_GET(B, t + 1);
;                     SC_STEP(A, t);
;                     if (t + 2 < SC_T) SC_GET(A, t + 2);
;                     SC_STEP(B, t + 1);
;                 }
	v_pk_mul_f32 v[106:107], v[64:65], v[44:45] op_sel_hi:[1,0]
	ds_read_b128 v[72:75], v175 offset:29440
	v_pk_mul_f32 v[108:109], v[64:65], v[56:57] op_sel_hi:[1,0]
	ds_read_b128 v[76:79], v175 offset:29456
	v_pk_fma_f32 v[106:107], v[66:67], v[44:45], v[106:107] op_sel:[0,1,0]
	ds_read_b128 v[80:83], v175 offset:29472
	v_pk_fma_f32 v[108:109], v[66:67], v[56:57], v[108:109] op_sel:[0,1,0]
	ds_read_b128 v[84:87], v175 offset:29488
	v_pk_fma_f32 v[106:107], v[68:69], v[46:47], v[106:107] op_sel_hi:[1,0,1]
	ds_read_b128 v[88:91], v175 offset:29504
	v_pk_fma_f32 v[108:109], v[68:69], v[58:59], v[108:109] op_sel_hi:[1,0,1]
	ds_read_b128 v[92:95], v123 offset:46848
	v_pk_fma_f32 v[106:107], v[70:71], v[46:47], v[106:107] op_sel:[0,1,0]
	v_pk_fma_f32 v[108:109], v[70:71], v[58:59], v[108:109] op_sel:[0,1,0]
	v_pk_mul_f32 v[110:111], v[64:65], v[40:41] op_sel_hi:[1,0]
	v_add_f32_dpp v106, v106, v106 quad_perm:[1,0,3,2] row_mask:0xf bank_mask:0xf bound_ctrl:1
	v_add_f32_dpp v107, v107, v107 quad_perm:[1,0,3,2] row_mask:0xf bank_mask:0xf bound_ctrl:1
	v_pk_fma_f32 v[108:109], v[62:63], v[176:177], v[108:109]
	v_pk_mul_f32 v[112:113], v[66:67], v[40:41] op_sel:[0,1]
	v_add_f32_dpp v106, v106, v106 quad_perm:[2,3,0,1] row_mask:0xf bank_mask:0xf bound_ctrl:1
	v_add_f32_dpp v107, v107, v107 quad_perm:[2,3,0,1] row_mask:0xf bank_mask:0xf bound_ctrl:1
	v_add_f32_dpp v148, v108, v108 row_half_mirror row_mask:0xf bank_mask:0xf bound_ctrl:1
	v_add_f32_dpp v148, v109, v109 row_half_mirror row_mask:0xf bank_mask:0xa
	v_add_f32_dpp v106, v106, v106 row_half_mirror row_mask:0xf bank_mask:0xf bound_ctrl:1
	v_add_f32_dpp v107, v107, v107 row_half_mirror row_mask:0xf bank_mask:0xf bound_ctrl:1
	v_pk_mul_f32 v[144:145], v[68:69], v[42:43] op_sel_hi:[1,0]
	v_pk_mul_f32 v[146:147], v[70:71], v[42:43] op_sel:[0,1]
	v_add_f32_dpp v106, v106, v106 row_mirror row_mask:0xf bank_mask:0xf bound_ctrl:1
	v_add_f32_dpp v107, v107, v107 row_mirror row_mask:0xf bank_mask:0xf bound_ctrl:1
	v_pk_fma_f32 v[110:111], v[60:61], v[52:53], v[110:111] op_sel_hi:[1,0,1]
	v_pk_fma_f32 v[112:113], v[60:61], v[52:53], v[112:113] op_sel:[0,1,0]
	v_pk_fma_f32 v[144:145], v[60:61], v[54:55], v[144:145] op_sel_hi:[1,0,1]
	v_pk_fma_f32 v[146:147], v[60:61], v[54:55], v[146:147] op_sel:[0,1,0]
	v_pk_fma_f32 v[64:65], v[106:107], v[48:49], v[110:111] op_sel_hi:[1,0,1]
	v_pk_fma_f32 v[66:67], v[106:107], v[48:49], v[112:113] op_sel:[0,1,0]
	v_pk_fma_f32 v[68:69], v[106:107], v[50:51], v[144:145] op_sel_hi:[1,0,1]
	v_pk_fma_f32 v[70:71], v[106:107], v[50:51], v[146:147] op_sel:[0,1,0]
	s_waitcnt lgkmcnt(0)
	v_pk_mul_f32 v[106:107], v[64:65], v[76:77] op_sel_hi:[1,0]
	ds_read_b128 v[40:43], v175 offset:30720
	v_pk_mul_f32 v[108:109], v[64:65], v[88:89] op_sel_hi:[1,0]
	ds_read_b128 v[44:47], v175 offset:30736
	v_pk_fma_f32 v[106:107], v[66:67], v[76:77], v[106:107] op_sel:[0,1,0]
	ds_read_b128 v[48:51], v175 offset:30752
	v_pk_fma_f32 v[108:109], v[66:67], v[88:89], v[108:109] op_sel:[0,1,0]
	ds_read_b128 v[52:55], v175 offset:30768
	v_pk_fma_f32 v[106:107], v[68:69], v[78:79], v[106:107] op_sel_hi:[1,0,1]
	ds_read_b128 v[56:59], v175 offset:30784
	v_pk_fma_f32 v[108:109], v[68:69], v[90:91], v[108:109] op_sel_hi:[1,0,1]
	ds_read_b128 v[60:63], v123 offset:47104
	v_pk_fma_f32 v[106:107], v[70:71], v[78:79], v[106:107] op_sel:[0,1,0]
	v_pk_fma_f32 v[108:109], v[70:71], v[90:91], v[108:109] op_sel:[0,1,0]
	v_pk_mul_f32 v[110:111], v[64:65], v[72:73] op_sel_hi:[1,0]
	v_add_f32_dpp v106, v106, v106 quad_perm:[1,0,3,2] row_mask:0xf bank_mask:0xf bound_ctrl:1
	v_add_f32_dpp v107, v107, v107 quad_perm:[1,0,3,2] row_mask:0xf bank_mask:0xf bound_ctrl:1
	v_pk_fma_f32 v[108:109], v[94:95], v[176:177], v[108:109]
	v_pk_mul_f32 v[112:113], v[66:67], v[72:73] op_sel:[0,1]
	v_add_f32_dpp v106, v106, v106 quad_perm:[2,3,0,1] row_mask:0xf bank_mask:0xf bound_ctrl:1
	v_add_f32_dpp v107, v107, v107 quad_perm:[2,3,0,1] row_mask:0xf bank_mask:0xf bound_ctrl:1
	v_add_f32_dpp v149, v108, v108 row_half_mirror row_mask:0xf bank_mask:0xf bound_ctrl:1
	v_add_f32_dpp v149, v109, v109 row_half_mirror row_mask:0xf bank_mask:0xa
	v_add_f32_dpp v106, v106, v106 row_half_mirror row_mask:0xf bank_mask:0xf bound_ctrl:1
	v_add_f32_dpp v107, v107, v107 row_half_mirror row_mask:0xf bank_mask:0xf bound_ctrl:1
	v_pk_mul_f32 v[144:145], v[68:69], v[74:75] op_sel_hi:[1,0]
	v_pk_mul_f32 v[146:147], v[70:71], v[74:75] op_sel:[0,1]
	v_add_f32_dpp v150, v148, v148 row_ror:8 row_mask:0xf bank_mask:0xf bound_ctrl:1
	v_add_f32_dpp v150, v149, v149 row_ror:8 row_mask:0xf bank_mask:0xc
	v_add_f32_dpp v106, v106, v106 row_mirror row_mask:0xf bank_mask:0xf bound_ctrl:1
	v_add_f32_dpp v107, v107, v107 row_mirror row_mask:0xf bank_mask:0xf bound_ctrl:1
	v_pk_fma_f32 v[110:111], v[92:93], v[84:85], v[110:111] op_sel_hi:[1,0,1]
	v_pk_fma_f32 v[112:113], v[92:93], v[84:85], v[112:113] op_sel:[0,1,0]
	v_pk_fma_f32 v[144:145], v[92:93], v[86:87], v[144:145] op_sel_hi:[1,0,1]
	v_pk_fma_f32 v[146:147], v[92:93], v[86:87], v[146:147] op_sel:[0,1,0]
	v_add_f32_dpp v150, v150, v150 quad_perm:[1,0,3,2] row_mask:0xf bank_mask:0xf bound_ctrl:1
	v_pk_fma_f32 v[64:65], v[106:107], v[80:81], v[110:111] op_sel_hi:[1,0,1]
	v_pk_fma_f32 v[66:67], v[106:107], v[80:81], v[112:113] op_sel:[0,1,0]
	v_add_f32_dpp v150, v150, v150 quad_perm:[2,3,0,1] row_mask:0xf bank_mask:0xf bound_ctrl:1
	v_pk_fma_f32 v[68:69], v[106:107], v[82:83], v[144:145] op_sel_hi:[1,0,1]
	v_pk_fma_f32 v[70:71], v[106:107], v[82:83], v[146:147] op_sel:[0,1,0]
	s_mov_b64 exec, s[34:35]
	ds_write_b32 v178, v150 offset:2816
	s_mov_b64 exec, -1
	s_waitcnt lgkmcnt(1)
; #define SC_GET(X, t) do { const float* p = rec + (t) * 320; w##X = *(const f32x4*)p; a##X = *(const f32x4*)(p + 4); b##X = *(const f32x4*)(p + 8); k##X = *(const f32x4*)(p + 12); q##X = *(const f32x4*)(p + 16); \
;                 v##X = *(const f32x4*)(VVa + (t) * 64); } while (0)
; DI void scan_phase(unsigned char* lds, const Ctx& a, const Op& d, const int variant) {
;     ...
;                 SC_GET(A, 0);
; #pragma unroll 2
;                 for (int t = 0; t < SC_T; t += 2) {
;                     SC_GET(B, t + 1);
;                     SC_STEP(A, t);
;                     if (t + 2 < SC_T) SC_GET(A, t + 2);
;                     SC_STEP(B, t + 1);
;                 }
	v_pk_mul_f32 v[106:107], v[64:65], v[44:45] op_sel_hi:[1,0]
	ds_read_b128 v[72:75], v175 offset:32000
	v_pk_mul_f32 v[108:109], v[64:65], v[56:57] op_sel_hi:[1,0]
	ds_read_b128 v[76:79], v175 offset:32016
	v_pk_fma_f32 v[106:107], v[66:67], v[44:45], v[106:107] op_sel:[0,1,0]
	ds_read_b128 v[80:83], v175 offset:32032
	v_pk_fma_f32 v[108:109], v[66:67], v[56:57], v[108:109] op_sel:[0,1,0]
	ds_read_b128 v[84:87], v175 offset:32048
	v_pk_fma_f32 v[106:107], v[68:69], v[46:47], v[106:107] op_sel_hi:[1,0,1]
	ds_read_b128 v[88:91], v175 offset:32064
	v_pk_fma_f32 v[108:109], v[68:69], v[58:59], v[108:109] op_sel_hi:[1,0,1]
	ds_read_b128 v[92:95], v123 offset:47360
	v_pk_fma_f32 v[106:107], v[70:71], v[46:47], v[106:107] op_sel:[0,1,0]
	v_pk_fma_f32 v[108:109], v[70:71], v[58:59], v[108:109] op_sel:[0,1,0]
	v_pk_mul_f32 v[110:111], v[64:65], v[40:41] op_sel_hi:[1,0]
	v_add_f32_dpp v106, v106, v106 quad_perm:[1,0,3,2] row_mask:0xf bank_mask:0xf bound_ctrl:1
	v_add_f32_dpp v107, v107, v107 quad_perm:[1,0,3,2] row_mask:0xf bank_mask:0xf bound_ctrl:1
	v_pk_fma_f32 v[108:109], v[62:63], v[176:177], v[108:109]
	v_pk_mul_f32 v[112:113], v[66:67], v[40:41] op_sel:[0,1]
	v_add_f32_dpp v106, v106, v106 quad_perm:[2,3,0,1] row_mask:0xf bank_mask:0xf bound_ctrl:1
	v_add_f32_dpp v107, v107, v107 quad_perm:[2,3,0,1] row_mask:0xf bank_mask:0xf bound_ctrl:1
	v_add_f32_dpp v148, v108, v108 row_half_mirror row_mask:0xf bank_mask:0xf bound_ctrl:1
	v_add_f32_dpp v148, v109, v109 row_half_mirror row_mask:0xf bank_mask:0xa
	v_add_f32_dpp v106, v106, v106 row_half_mirror row_mask:0xf bank_mask:0xf bound_ctrl:1
	v_add_f32_dpp v107, v107, v107 row_half_mirror row_mask:0xf bank_mask:0xf bound_ctrl:1
	v_pk_mul_f32 v[144:145], v[68:69], v[42:43] op_sel_hi:[1,0]
	v_pk_mul_f32 v[146:147], v[70:71], v[42:43] op_sel:[0,1]
	v_add_f32_dpp v106, v106, v106 row_mirror row_mask:0xf bank_mask:0xf bound_ctrl:1
	v_add_f32_dpp v107, v107, v107 row_mirror row_mask:0xf bank_mask:0xf bound_ctrl:1
	v_pk_fma_f32 v[110:111], v[60:61], v[52:53], v[110:111] op_sel_hi:[1,0,1]
	v_pk_fma_f32 v[112:113], v[60:61], v[52:53], v[112:113] op_sel:[0,1,0]
	v_pk_fma_f32 v[144:145], v[60:61], v[54:55], v[144:145] op_sel_hi:[1,0,1]
	v_pk_fma_f32 v[146:147], v[60:61], v[54:55], v[146:147] op_sel:[0,1,0]
	v_pk_fma_f32 v[64:65], v[106:107], v[48:49], v[110:111] op_sel_hi:[1,0,1]
	v_pk_fma_f32 v[66:67], v[106:107], v[48:49], v[112:113] op_sel:[0,1,0]
	v_pk_fma_f32 v[68:69], v[106:107], v[50:51], v[144:145] op_sel_hi:[1,0,1]
	v_pk_fma_f32 v[70:71], v[106:107], v[50:51], v[146:147] op_sel:[0,1,0]
	s_waitcnt lgkmcnt(0)
	v_pk_mul_f32 v[106:107], v[64:65], v[76:77] op_sel_hi:[1,0]
	ds_read_b128 v[40:43], v175 offset:33280
	v_pk_mul_f32 v[108:109], v[64:65], v[88:89] op_sel_hi:[1,0]
	ds_read_b128 v[44:47], v175 offset:33296
	v_pk_fma_f32 v[106:107], v[66:67], v[76:77], v[106:107] op_sel:[0,1,0]
	ds_read_b128 v[48:51], v175 offset:33312
	v_pk_fma_f32 v[108:109], v[66:67], v[88:89], v[108:109] op_sel:[0,1,0]
	ds_read_b128 v[52:55], v175 offset:33328
	v_pk_fma_f32 v[106:107], v[68:69], v[78:79], v[106:107] op_sel_hi:[1,0,1]
	ds_read_b128 v[56:59], v175 offset:33344
	v_pk_fma_f32 v[108:109], v[68:69], v[90:91], v[108:109] op_sel_hi:[1,0,1]
	ds_read_b128 v[60:63], v123 offset:47616
	v_pk_fma_f32 v[106:107], v[70:71], v[78:79], v[106:107] op_sel:[0,1,0]
	v_pk_fma_f32 v[108:109], v[70:71], v[90:91], v[108:109] op_sel:[0,1,0]
	v_pk_mul_f32 v[110:111], v[64:65], v[72:73] op_sel_hi:[1,0]
	v_add_f32_dpp v106, v106, v106 quad_perm:[1,0,3,2] row_mask:0xf bank_mask:0xf bound_ctrl:1
	v_add_f32_dpp v107, v107, v107 quad_perm:[1,0,3,2] row_mask:0xf bank_mask:0xf bound_ctrl:1
	v_pk_fma_f32 v[108:109], v[94:95], v[176:177], v[108:109]
	v_pk_mul_f32 v[112:113], v[66:67], v[72:73] op_sel:[0,1]
	v_add_f32_dpp v106, v106, v106 quad_perm:[2,3,0,1] row_mask:0xf bank_mask:0xf bound_ctrl:1
	v_add_f32_dpp v107, v107, v107 quad_perm:[2,3,0,1] row_mask:0xf bank_mask:0xf bound_ctrl:1
	v_add_f32_dpp v149, v108, v108 row_half_mirror row_mask:0xf bank_mask:0xf bound_ctrl:1
	v_add_f32_dpp v149, v109, v109 row_half_mirror row_mask:0xf bank_mask:0xa
	v_add_f32_dpp v106, v106, v106 row_half_mirror row_mask:0xf bank_mask:0xf bound_ctrl:1
	v_add_f32_dpp v107, v107, v107 row_half_mirror row_mask:0xf bank_mask:0xf bound_ctrl:1
	v_pk_mul_f32 v[144:145], v[68:69], v[74:75] op_sel_hi:[1,0]
	v_pk_mul_f32 v[146:147], v[70:71], v[74:75] op_sel:[0,1]
	v_add_f32_dpp v150, v148, v148 row_ror:8 row_mask:0xf bank_mask:0xf bound_ctrl:1
	v_add_f32_dpp v150, v149, v149 row_ror:8 row_mask:0xf bank_mask:0xc
	v_add_f32_dpp v106, v106, v106 row_mirror row_mask:0xf bank_mask:0xf bound_ctrl:1
	v_add_f32_dpp v107, v107, v107 row_mirror row_mask:0xf bank_mask:0xf bound_ctrl:1
	v_pk_fma_f32 v[110:111], v[92:93], v[84:85], v[110:111] op_sel_hi:[1,0,1]
	v_pk_fma_f32 v[112:113], v[92:93], v[84:85], v[112:113] op_sel:[0,1,0]
	v_pk_fma_f32 v[144:145], v[92:93], v[86:87], v[144:145] op_sel_hi:[1,0,1]
	v_pk_fma_f32 v[146:147], v[92:93], v[86:87], v[146:147] op_sel:[0,1,0]
	v_add_f32_dpp v150, v150, v150 quad_perm:[1,0,3,2] row_mask:0xf bank_mask:0xf bound_ctrl:1
	v_pk_fma_f32 v[64:65], v[106:107], v[80:81], v[110:111] op_sel_hi:[1,0,1]
	v_pk_fma_f32 v[66:67], v[106:107], v[80:81], v[112:113] op_sel:[0,1,0]
	v_add_f32_dpp v150, v150, v150 quad_perm:[2,3,0,1] row_mask:0xf bank_mask:0xf bound_ctrl:1
	v_pk_fma_f32 v[68:69], v[106:107], v[82:83], v[144:145] op_sel_hi:[1,0,1]
	v_pk_fma_f32 v[70:71], v[106:107], v[82:83], v[146:147] op_sel:[0,1,0]
	s_mov_b64 exec, s[34:35]
	ds_write_b32 v178, v150 offset:3072
	s_mov_b64 exec, -1
	s_waitcnt lgkmcnt(1)
; #define SC_GET(X, t) do { const float* p = rec + (t) * 320; w##X = *(const f32x4*)p; a##X = *(const f32x4*)(p + 4); b##X = *(const f32x4*)(p + 8); k##X = *(const f32x4*)(p + 12); q##X = *(const f32x4*)(p + 16); \
;                 v##X = *(const f32x4*)(VVa + (t) * 64); } while (0)
; DI void scan_phase(unsigned char* lds, const Ctx& a, const Op& d, const int variant) {
;     ...
;                 SC_GET(A, 0);
; #pragma unroll 2
;                 for (int t = 0; t < SC_T; t += 2) {
;                     SC_GET(B, t + 1);
;                     SC_STEP(A, t);
;                     if (t + 2 < SC_T) SC_GET(A, t + 2);
;                     SC_STEP(B, t + 1);
;                 }
	v_pk_mul_f32 v[106:107], v[64:65], v[44:45] op_sel_hi:[1,0]
	ds_read_b128 v[72:75], v175 offset:34560
	v_pk_mul_f32 v[108:109], v[64:65], v[56:57] op_sel_hi:[1,0]
	ds_read_b128 v[76:79], v175 offset:34576
	v_pk_fma_f32 v[106:107], v[66:67], v[44:45], v[106:107] op_sel:[0,1,0]
	ds_read_b128 v[80:83], v175 offset:34592
	v_pk_fma_f32 v[108:109], v[66:67], v[56:57], v[108:109] op_sel:[0,1,0]
	ds_read_b128 v[84:87], v175 offset:34608
	v_pk_fma_f32 v[106:107], v[68:69], v[46:47], v[106:107] op_sel_hi:[1,0,1]
	ds_read_b128 v[88:91], v175 offset:34624
	v_pk_fma_f32 v[108:109], v[68:69], v[58:59], v[108:109] op_sel_hi:[1,0,1]
	ds_read_b128 v[92:95], v123 offset:47872
	v_pk_fma_f32 v[106:107], v[70:71], v[46:47], v[106:107] op_sel:[0,1,0]
	v_pk_fma_f32 v[108:109], v[70:71], v[58:59], v[108:109] op_sel:[0,1,0]
	v_pk_mul_f32 v[110:111], v[64:65], v[40:41] op_sel_hi:[1,0]
	v_add_f32_dpp v106, v106, v106 quad_perm:[1,0,3,2] row_mask:0xf bank_mask:0xf bound_ctrl:1
	v_add_f32_dpp v107, v107, v107 quad_perm:[1,0,3,2] row_mask:0xf bank_mask:0xf bound_ctrl:1
	v_pk_fma_f32 v[108:109], v[62:63], v[176:177], v[108:109]
	v_pk_mul_f32 v[112:113], v[66:67], v[40:41] op_sel:[0,1]
	v_add_f32_dpp v106, v106, v106 quad_perm:[2,3,0,1] row_mask:0xf bank_mask:0xf bound_ctrl:1
	v_add_f32_dpp v107, v107, v107 quad_perm:[2,3,0,1] row_mask:0xf bank_mask:0xf bound_ctrl:1
	v_add_f32_dpp v148, v108, v108 row_half_mirror row_mask:0xf bank_mask:0xf bound_ctrl:1
	v_add_f32_dpp v148, v109, v109 row_half_mirror row_mask:0xf bank_mask:0xa
	v_add_f32_dpp v106, v106, v106 row_half_mirror row_mask:0xf bank_mask:0xf bound_ctrl:1
	v_add_f32_dpp v107, v107, v107 row_half_mirror row_mask:0xf bank_mask:0xf bound_ctrl:1
	v_pk_mul_f32 v[144:145], v[68:69], v[42:43] op_sel_hi:[1,0]
	v_pk_mul_f32 v[146:147], v[70:71], v[42:43] op_sel:[0,1]
	v_add_f32_dpp v106, v106, v106 row_mirror row_mask:0xf bank_mask:0xf bound_ctrl:1
	v_add_f32_dpp v107, v107, v107 row_mirror row_mask:0xf bank_mask:0xf bound_ctrl:1
	v_pk_fma_f32 v[110:111], v[60:61], v[52:53], v[110:111] op_sel_hi:[1,0,1]
	v_pk_fma_f32 v[112:113], v[60:61], v[52:53], v[112:113] op_sel:[0,1,0]
	v_pk_fma_f32 v[144:145], v[60:61], v[54:55], v[144:145] op_sel_hi:[1,0,1]
	v_pk_fma_f32 v[146:147], v[60:61], v[54:55], v[146:147] op_sel:[0,1,0]
	v_pk_fma_f32 v[64:65], v[106:107], v[48:49], v[110:111] op_sel_hi:[1,0,1]
	v_pk_fma_f32 v[66:67], v[106:107], v[48:49], v[112:113] op_sel:[0,1,0]
	v_pk_fma_f32 v[68:69], v[106:107], v[50:51], v[144:145] op_sel_hi:[1,0,1]
	v_pk_fma_f32 v[70:71], v[106:107], v[50:51], v[146:147] op_sel:[0,1,0]
	s_waitcnt lgkmcnt(0)
	v_pk_mul_f32 v[106:107], v[64:65], v[76:77] op_sel_hi:[1,0]
	ds_read_b128 v[40:43], v175 offset:35840
	v_pk_mul_f32 v[108:109], v[64:65], v[88:89] op_sel_hi:[1,0]
	ds_read_b128 v[44:47], v175 offset:35856
	v_pk_fma_f32 v[106:107], v[66:67], v[76:77], v[106:107] op_sel:[0,1,0]
	ds_read_b128 v[48:51], v175 offset:35872
	v_pk_fma_f32 v[108:109], v[66:67], v[88:89], v[108:109] op_sel:[0,1,0]
	ds_read_b128 v[52:55], v175 offset:35888
	v_pk_fma_f32 v[106:107], v[68:69], v[78:79], v[106:107] op_sel_hi:[1,0,1]
	ds_read_b128 v[56:59], v175 offset:35904
	v_pk_fma_f32 v[108:109], v[68:69], v[90:91], v[108:109] op_sel_hi:[1,0,1]
	ds_read_b128 v[60:63], v123 offset:48128
	v_pk_fma_f32 v[106:107], v[70:71], v[78:79], v[106:107] op_sel:[0,1,0]
	v_pk_fma_f32 v[108:109], v[70:71], v[90:91], v[108:109] op_sel:[0,1,0]
	v_pk_mul_f32 v[110:111], v[64:65], v[72:73] op_sel_hi:[1,0]
	v_add_f32_dpp v106, v106, v106 quad_perm:[1,0,3,2] row_mask:0xf bank_mask:0xf bound_ctrl:1
	v_add_f32_dpp v107, v107, v107 quad_perm:[1,0,3,2] row_mask:0xf bank_mask:0xf bound_ctrl:1
	v_pk_fma_f32 v[108:109], v[94:95], v[176:177], v[108:109]
	v_pk_mul_f32 v[112:113], v[66:67], v[72:73] op_sel:[0,1]
	v_add_f32_dpp v106, v106, v106 quad_perm:[2,3,0,1] row_mask:0xf bank_mask:0xf bound_ctrl:1
	v_add_f32_dpp v107, v107, v107 quad_perm:[2,3,0,1] row_mask:0xf bank_mask:0xf bound_ctrl:1
	v_add_f32_dpp v149, v108, v108 row_half_mirror row_mask:0xf bank_mask:0xf bound_ctrl:1
	v_add_f32_dpp v149, v109, v109 row_half_mirror row_mask:0xf bank_mask:0xa
	v_add_f32_dpp v106, v106, v106 row_half_mirror row_mask:0xf bank_mask:0xf bound_ctrl:1
	v_add_f32_dpp v107, v107, v107 row_half_mirror row_mask:0xf bank_mask:0xf bound_ctrl:1
	v_pk_mul_f32 v[144:145], v[68:69], v[74:75] op_sel_hi:[1,0]
	v_pk_mul_f32 v[146:147], v[70:71], v[74:75] op_sel:[0,1]
	v_add_f32_dpp v150, v148, v148 row_ror:8 row_mask:0xf bank_mask:0xf bound_ctrl:1
	v_add_f32_dpp v150, v149, v149 row_ror:8 row_mask:0xf bank_mask:0xc
	v_add_f32_dpp v106, v106, v106 row_mirror row_mask:0xf bank_mask:0xf bound_ctrl:1
	v_add_f32_dpp v107, v107, v107 row_mirror row_mask:0xf bank_mask:0xf bound_ctrl:1
	v_pk_fma_f32 v[110:111], v[92:93], v[84:85], v[110:111] op_sel_hi:[1,0,1]
	v_pk_fma_f32 v[112:113], v[92:93], v[84:85], v[112:113] op_sel:[0,1,0]
	v_pk_fma_f32 v[144:145], v[92:93], v[86:87], v[144:145] op_sel_hi:[1,0,1]
	v_pk_fma_f32 v[146:147], v[92:93], v[86:87], v[146:147] op_sel:[0,1,0]
	v_add_f32_dpp v150, v150, v150 quad_perm:[1,0,3,2] row_mask:0xf bank_mask:0xf bound_ctrl:1
	v_pk_fma_f32 v[64:65], v[106:107], v[80:81], v[110:111] op_sel_hi:[1,0,1]
	v_pk_fma_f32 v[66:67], v[106:107], v[80:81], v[112:113] op_sel:[0,1,0]
	v_add_f32_dpp v150, v150, v150 quad_perm:[2,3,0,1] row_mask:0xf bank_mask:0xf bound_ctrl:1
	v_pk_fma_f32 v[68:69], v[106:107], v[82:83], v[144:145] op_sel_hi:[1,0,1]
	v_pk_fma_f32 v[70:71], v[106:107], v[82:83], v[146:147] op_sel:[0,1,0]
	s_mov_b64 exec, s[34:35]
	ds_write_b32 v178, v150 offset:3328
	s_mov_b64 exec, -1
	s_waitcnt lgkmcnt(1)
; #define SC_GET(X, t) do { const float* p = rec + (t) * 320; w##X = *(const f32x4*)p; a##X = *(const f32x4*)(p + 4); b##X = *(const f32x4*)(p + 8); k##X = *(const f32x4*)(p + 12); q##X = *(const f32x4*)(p + 16); \
;                 v##X = *(const f32x4*)(VVa + (t) * 64); } while (0)
; DI void scan_phase(unsigned char* lds, const Ctx& a, const Op& d, const int variant) {
;     ...
;                 SC_GET(A, 0);
; #pragma unroll 2
;                 for (int t = 0; t < SC_T; t += 2) {
;                     SC_GET(B, t + 1);
;                     SC_STEP(A, t);
;                     if (t + 2 < SC_T) SC_GET(A, t + 2);
;                     SC_STEP(B, t + 1);
;                 }
	v_pk_mul_f32 v[106:107], v[64:65], v[44:45] op_sel_hi:[1,0]
	ds_read_b128 v[72:75], v175 offset:37120
	v_pk_mul_f32 v[108:109], v[64:65], v[56:57] op_sel_hi:[1,0]
	ds_read_b128 v[76:79], v175 offset:37136
	v_pk_fma_f32 v[106:107], v[66:67], v[44:45], v[106:107] op_sel:[0,1,0]
	ds_read_b128 v[80:83], v175 offset:37152
	v_pk_fma_f32 v[108:109], v[66:67], v[56:57], v[108:109] op_sel:[0,1,0]
	ds_read_b128 v[84:87], v175 offset:37168
	v_pk_fma_f32 v[106:107], v[68:69], v[46:47], v[106:107] op_sel_hi:[1,0,1]
	ds_read_b128 v[88:91], v175 offset:37184
	v_pk_fma_f32 v[108:109], v[68:69], v[58:59], v[108:109] op_sel_hi:[1,0,1]
	ds_read_b128 v[92:95], v123 offset:48384
	v_pk_fma_f32 v[106:107], v[70:71], v[46:47], v[106:107] op_sel:[0,1,0]
	v_pk_fma_f32 v[108:109], v[70:71], v[58:59], v[108:109] op_sel:[0,1,0]
	v_pk_mul_f32 v[110:111], v[64:65], v[40:41] op_sel_hi:[1,0]
	v_add_f32_dpp v106, v106, v106 quad_perm:[1,0,3,2] row_mask:0xf bank_mask:0xf bound_ctrl:1
	v_add_f32_dpp v107, v107, v107 quad_perm:[1,0,3,2] row_mask:0xf bank_mask:0xf bound_ctrl:1
	v_pk_fma_f32 v[108:109], v[62:63], v[176:177], v[108:109]
	v_pk_mul_f32 v[112:113], v[66:67], v[40:41] op_sel:[0,1]
	v_add_f32_dpp v106, v106, v106 quad_perm:[2,3,0,1] row_mask:0xf bank_mask:0xf bound_ctrl:1
	v_add_f32_dpp v107, v107, v107 quad_perm:[2,3,0,1] row_mask:0xf bank_mask:0xf bound_ctrl:1
	v_add_f32_dpp v148, v108, v108 row_half_mirror row_mask:0xf bank_mask:0xf bound_ctrl:1
	v_add_f32_dpp v148, v109, v109 row_half_mirror row_mask:0xf bank_mask:0xa
	v_add_f32_dpp v106, v106, v106 row_half_mirror row_mask:0xf bank_mask:0xf bound_ctrl:1
	v_add_f32_dpp v107, v107, v107 row_half_mirror row_mask:0xf bank_mask:0xf bound_ctrl:1
	v_pk_mul_f32 v[144:145], v[68:69], v[42:43] op_sel_hi:[1,0]
	v_pk_mul_f32 v[146:147], v[70:71], v[42:43] op_sel:[0,1]
	v_add_f32_dpp v106, v106, v106 row_mirror row_mask:0xf bank_mask:0xf bound_ctrl:1
	v_add_f32_dpp v107, v107, v107 row_mirror row_mask:0xf bank_mask:0xf bound_ctrl:1
	v_pk_fma_f32 v[110:111], v[60:61], v[52:53], v[110:111] op_sel_hi:[1,0,1]
	v_pk_fma_f32 v[112:113], v[60:61], v[52:53], v[112:113] op_sel:[0,1,0]
	v_pk_fma_f32 v[144:145], v[60:61], v[54:55], v[144:145] op_sel_hi:[1,0,1]
	v_pk_fma_f32 v[146:147], v[60:61], v[54:55], v[146:147] op_sel:[0,1,0]
	v_pk_fma_f32 v[64:65], v[106:107], v[48:49], v[110:111] op_sel_hi:[1,0,1]
	v_pk_fma_f32 v[66:67], v[106:107], v[48:49], v[112:113] op_sel:[0,1,0]
	v_pk_fma_f32 v[68:69], v[106:107], v[50:51], v[144:145] op_sel_hi:[1,0,1]
	v_pk_fma_f32 v[70:71], v[106:107], v[50:51], v[146:147] op_sel:[0,1,0]
	s_waitcnt lgkmcnt(0)
	v_pk_mul_f32 v[106:107], v[64:65], v[76:77] op_sel_hi:[1,0]
	ds_read_b128 v[40:43], v175 offset:38400
	v_pk_mul_f32 v[108:109], v[64:65], v[88:89] op_sel_hi:[1,0]
	ds_read_b128 v[44:47], v175 offset:38416
	v_pk_fma_f32 v[106:107], v[66:67], v[76:77], v[106:107] op_sel:[0,1,0]
	ds_read_b128 v[48:51], v175 offset:38432
	v_pk_fma_f32 v[108:109], v[66:67], v[88:89], v[108:109] op_sel:[0,1,0]
	ds_read_b128 v[52:55], v175 offset:38448
	v_pk_fma_f32 v[106:107], v[68:69], v[78:79], v[106:107] op_sel_hi:[1,0,1]
	ds_read_b128 v[56:59], v175 offset:38464
	v_pk_fma_f32 v[108:109], v[68:69], v[90:91], v[108:109] op_sel_hi:[1,0,1]
	ds_read_b128 v[60:63], v123 offset:48640
	v_pk_fma_f32 v[106:107], v[70:71], v[78:79], v[106:107] op_sel:[0,1,0]
	v_pk_fma_f32 v[108:109], v[70:71], v[90:91], v[108:109] op_sel:[0,1,0]
	v_pk_mul_f32 v[110:111], v[64:65], v[72:73] op_sel_hi:[1,0]
	v_add_f32_dpp v106, v106, v106 quad_perm:[1,0,3,2] row_mask:0xf bank_mask:0xf bound_ctrl:1
	v_add_f32_dpp v107, v107, v107 quad_perm:[1,0,3,2] row_mask:0xf bank_mask:0xf bound_ctrl:1
	v_pk_fma_f32 v[108:109], v[94:95], v[176:177], v[108:109]
	v_pk_mul_f32 v[112:113], v[66:67], v[72:73] op_sel:[0,1]
	v_add_f32_dpp v106, v106, v106 quad_perm:[2,3,0,1] row_mask:0xf bank_mask:0xf bound_ctrl:1
	v_add_f32_dpp v107, v107, v107 quad_perm:[2,3,0,1] row_mask:0xf bank_mask:0xf bound_ctrl:1
	v_add_f32_dpp v149, v108, v108 row_half_mirror row_mask:0xf bank_mask:0xf bound_ctrl:1
	v_add_f32_dpp v149, v109, v109 row_half_mirror row_mask:0xf bank_mask:0xa
	v_add_f32_dpp v106, v106, v106 row_half_mirror row_mask:0xf bank_mask:0xf bound_ctrl:1
	v_add_f32_dpp v107, v107, v107 row_half_mirror row_mask:0xf bank_mask:0xf bound_ctrl:1
	v_pk_mul_f32 v[144:145], v[68:69], v[74:75] op_sel_hi:[1,0]
	v_pk_mul_f32 v[146:147], v[70:71], v[74:75] op_sel:[0,1]
	v_add_f32_dpp v150, v148, v148 row_ror:8 row_mask:0xf bank_mask:0xf bound_ctrl:1
	v_add_f32_dpp v150, v149, v149 row_ror:8 row_mask:0xf bank_mask:0xc
	v_add_f32_dpp v106, v106, v106 row_mirror row_mask:0xf bank_mask:0xf bound_ctrl:1
	v_add_f32_dpp v107, v107, v107 row_mirror row_mask:0xf bank_mask:0xf bound_ctrl:1
	v_pk_fma_f32 v[110:111], v[92:93], v[84:85], v[110:111] op_sel_hi:[1,0,1]
	v_pk_fma_f32 v[112:113], v[92:93], v[84:85], v[112:113] op_sel:[0,1,0]
	v_pk_fma_f32 v[144:145], v[92:93], v[86:87], v[144:145] op_sel_hi:[1,0,1]
	v_pk_fma_f32 v[146:147], v[92:93], v[86:87], v[146:147] op_sel:[0,1,0]
	v_add_f32_dpp v150, v150, v150 quad_perm:[1,0,3,2] row_mask:0xf bank_mask:0xf bound_ctrl:1
	v_pk_fma_f32 v[64:65], v[106:107], v[80:81], v[110:111] op_sel_hi:[1,0,1]
	v_pk_fma_f32 v[66:67], v[106:107], v[80:81], v[112:113] op_sel:[0,1,0]
	v_add_f32_dpp v150, v150, v150 quad_perm:[2,3,0,1] row_mask:0xf bank_mask:0xf bound_ctrl:1
	v_pk_fma_f32 v[68:69], v[106:107], v[82:83], v[144:145] op_sel_hi:[1,0,1]
	v_pk_fma_f32 v[70:71], v[106:107], v[82:83], v[146:147] op_sel:[0,1,0]
	s_mov_b64 exec, s[34:35]
	ds_write_b32 v178, v150 offset:3584
	s_mov_b64 exec, -1
	s_waitcnt lgkmcnt(1)
; #define SC_GET(X, t) do { const float* p = rec + (t) * 320; w##X = *(const f32x4*)p; a##X = *(const f32x4*)(p + 4); b##X = *(const f32x4*)(p + 8); k##X = *(const f32x4*)(p + 12); q##X = *(const f32x4*)(p + 16); \
;                 v##X = *(const f32x4*)(VVa + (t) * 64); } while (0)
; DI void scan_phase(unsigned char* lds, const Ctx& a, const Op& d, const int variant) {
;     ...
;                 SC_GET(A, 0);
; #pragma unroll 2
;                 for (int t = 0; t < SC_T; t += 2) {
;                     SC_GET(B, t + 1);
;                     SC_STEP(A, t);
;                     if (t + 2 < SC_T) SC_GET(A, t + 2);
;                     SC_STEP(B, t + 1);
;                 }
	v_pk_mul_f32 v[106:107], v[64:65], v[44:45] op_sel_hi:[1,0]
	ds_read_b128 v[72:75], v175 offset:39680
	v_pk_mul_f32 v[108:109], v[64:65], v[56:57] op_sel_hi:[1,0]
	ds_read_b128 v[76:79], v175 offset:39696
	v_pk_fma_f32 v[106:107], v[66:67], v[44:45], v[106:107] op_sel:[0,1,0]
	ds_read_b128 v[80:83], v175 offset:39712
	v_pk_fma_f32 v[108:109], v[66:67], v[56:57], v[108:109] op_sel:[0,1,0]
	ds_read_b128 v[84:87], v175 offset:39728
	v_pk_fma_f32 v[106:107], v[68:69], v[46:47], v[106:107] op_sel_hi:[1,0,1]
	ds_read_b128 v[88:91], v175 offset:39744
	v_pk_fma_f32 v[108:109], v[68:69], v[58:59], v[108:109] op_sel_hi:[1,0,1]
	ds_read_b128 v[92:95], v123 offset:48896
	v_pk_fma_f32 v[106:107], v[70:71], v[46:47], v[106:107] op_sel:[0,1,0]
	v_pk_fma_f32 v[108:109], v[70:71], v[58:59], v[108:109] op_sel:[0,1,0]
	v_pk_mul_f32 v[110:111], v[64:65], v[40:41] op_sel_hi:[1,0]
	v_add_f32_dpp v106, v106, v106 quad_perm:[1,0,3,2] row_mask:0xf bank_mask:0xf bound_ctrl:1
	v_add_f32_dpp v107, v107, v107 quad_perm:[1,0,3,2] row_mask:0xf bank_mask:0xf bound_ctrl:1
	v_pk_fma_f32 v[108:109], v[62:63], v[176:177], v[108:109]
	v_pk_mul_f32 v[112:113], v[66:67], v[40:41] op_sel:[0,1]
	v_add_f32_dpp v106, v106, v106 quad_perm:[2,3,0,1] row_mask:0xf bank_mask:0xf bound_ctrl:1
	v_add_f32_dpp v107, v107, v107 quad_perm:[2,3,0,1] row_mask:0xf bank_mask:0xf bound_ctrl:1
	v_add_f32_dpp v148, v108, v108 row_half_mirror row_mask:0xf bank_mask:0xf bound_ctrl:1
	v_add_f32_dpp v148, v109, v109 row_half_mirror row_mask:0xf bank_mask:0xa
	v_add_f32_dpp v106, v106, v106 row_half_mirror row_mask:0xf bank_mask:0xf bound_ctrl:1
	v_add_f32_dpp v107, v107, v107 row_half_mirror row_mask:0xf bank_mask:0xf bound_ctrl:1
	v_pk_mul_f32 v[144:145], v[68:69], v[42:43] op_sel_hi:[1,0]
	v_pk_mul_f32 v[146:147], v[70:71], v[42:43] op_sel:[0,1]
	v_add_f32_dpp v106, v106, v106 row_mirror row_mask:0xf bank_mask:0xf bound_ctrl:1
	v_add_f32_dpp v107, v107, v107 row_mirror row_mask:0xf bank_mask:0xf bound_ctrl:1
	v_pk_fma_f32 v[110:111], v[60:61], v[52:53], v[110:111] op_sel_hi:[1,0,1]
	v_pk_fma_f32 v[112:113], v[60:61], v[52:53], v[112:113] op_sel:[0,1,0]
	v_pk_fma_f32 v[144:145], v[60:61], v[54:55], v[144:145] op_sel_hi:[1,0,1]
	v_pk_fma_f32 v[146:147], v[60:61], v[54:55], v[146:147] op_sel:[0,1,0]
	v_pk_fma_f32 v[64:65], v[106:107], v[48:49], v[110:111] op_sel_hi:[1,0,1]
	v_pk_fma_f32 v[66:67], v[106:107], v[48:49], v[112:113] op_sel:[0,1,0]
	v_pk_fma_f32 v[68:69], v[106:107], v[50:51], v[144:145] op_sel_hi:[1,0,1]
	v_pk_fma_f32 v[70:71], v[106:107], v[50:51], v[146:147] op_sel:[0,1,0]
	s_waitcnt lgkmcnt(0)
	v_pk_mul_f32 v[106:107], v[64:65], v[76:77] op_sel_hi:[1,0]
	ds_read_b128 v[40:43], v175 offset:40960
	v_pk_mul_f32 v[108:109], v[64:65], v[88:89] op_sel_hi:[1,0]
	ds_read_b128 v[44:47], v175 offset:40976
	v_pk_fma_f32 v[106:107], v[66:67], v[76:77], v[106:107] op_sel:[0,1,0]
	ds_read_b128 v[48:51], v175 offset:40992
	v_pk_fma_f32 v[108:109], v[66:67], v[88:89], v[108:109] op_sel:[0,1,0]
	ds_read_b128 v[52:55], v175 offset:41008
	v_pk_fma_f32 v[106:107], v[68:69], v[78:79], v[106:107] op_sel_hi:[1,0,1]
	ds_read_b128 v[56:59], v175 offset:41024
	v_pk_fma_f32 v[108:109], v[68:69], v[90:91], v[108:109] op_sel_hi:[1,0,1]
	ds_read_b128 v[60:63], v123 offset:49152
	v_pk_fma_f32 v[106:107], v[70:71], v[78:79], v[106:107] op_sel:[0,1,0]
	v_pk_fma_f32 v[108:109], v[70:71], v[90:91], v[108:109] op_sel:[0,1,0]
	v_pk_mul_f32 v[110:111], v[64:65], v[72:73] op_sel_hi:[1,0]
	v_add_f32_dpp v106, v106, v106 quad_perm:[1,0,3,2] row_mask:0xf bank_mask:0xf bound_ctrl:1
	v_add_f32_dpp v107, v107, v107 quad_perm:[1,0,3,2] row_mask:0xf bank_mask:0xf bound_ctrl:1
	v_pk_fma_f32 v[108:109], v[94:95], v[176:177], v[108:109]
	v_pk_mul_f32 v[112:113], v[66:67], v[72:73] op_sel:[0,1]
	v_add_f32_dpp v106, v106, v106 quad_perm:[2,3,0,1] row_mask:0xf bank_mask:0xf bound_ctrl:1
	v_add_f32_dpp v107, v107, v107 quad_perm:[2,3,0,1] row_mask:0xf bank_mask:0xf bound_ctrl:1
	v_add_f32_dpp v149, v108, v108 row_half_mirror row_mask:0xf bank_mask:0xf bound_ctrl:1
	v_add_f32_dpp v149, v109, v109 row_half_mirror row_mask:0xf bank_mask:0xa
	v_add_f32_dpp v106, v106, v106 row_half_mirror row_mask:0xf bank_mask:0xf bound_ctrl:1
	v_add_f32_dpp v107, v107, v107 row_half_mirror row_mask:0xf bank_mask:0xf bound_ctrl:1
	v_pk_mul_f32 v[144:145], v[68:69], v[74:75] op_sel_hi:[1,0]
	v_pk_mul_f32 v[146:147], v[70:71], v[74:75] op_sel:[0,1]
	v_add_f32_dpp v150, v148, v148 row_ror:8 row_mask:0xf bank_mask:0xf bound_ctrl:1
	v_add_f32_dpp v150, v149, v149 row_ror:8 row_mask:0xf bank_mask:0xc
	v_add_f32_dpp v106, v106, v106 row_mirror row_mask:0xf bank_mask:0xf bound_ctrl:1
	v_add_f32_dpp v107, v107, v107 row_mirror row_mask:0xf bank_mask:0xf bound_ctrl:1
	v_pk_fma_f32 v[110:111], v[92:93], v[84:85], v[110:111] op_sel_hi:[1,0,1]
	v_pk_fma_f32 v[112:113], v[92:93], v[84:85], v[112:113] op_sel:[0,1,0]
	v_pk_fma_f32 v[144:145], v[92:93], v[86:87], v[144:145] op_sel_hi:[1,0,1]
	v_pk_fma_f32 v[146:147], v[92:93], v[86:87], v[146:147] op_sel:[0,1,0]
	v_add_f32_dpp v150, v150, v150 quad_perm:[1,0,3,2] row_mask:0xf bank_mask:0xf bound_ctrl:1
	v_pk_fma_f32 v[64:65], v[106:107], v[80:81], v[110:111] op_sel_hi:[1,0,1]
	v_pk_fma_f32 v[66:67], v[106:107], v[80:81], v[112:113] op_sel:[0,1,0]
	v_add_f32_dpp v150, v150, v150 quad_perm:[2,3,0,1] row_mask:0xf bank_mask:0xf bound_ctrl:1
	v_pk_fma_f32 v[68:69], v[106:107], v[82:83], v[144:145] op_sel_hi:[1,0,1]
	v_pk_fma_f32 v[70:71], v[106:107], v[82:83], v[146:147] op_sel:[0,1,0]
	s_mov_b64 exec, s[34:35]
	ds_write_b32 v178, v150 offset:3840
	s_mov_b64 exec, -1
	s_setprio 0
